# S5 pass 1 and pass 2 (MFMA-interleaved): every v_pk_fma/mul/add_f32 split into two scalar f32 ops (same per-lane arithmetic); carry phase keeps packed ops
# baseline (speedup 1.0000x reference)
; #define LAS __attribute__((address_space(3)))
; __device__ __forceinline__ bf16x8 pack8(f32x4 lo, f32x4 hi) { v4u w; w.x = pk2(lo[0], lo[1]); w.y = pk2(lo[2], lo[3]); w.z = pk2(hi[0], hi[1]); w.w = pk2(hi[2], hi[3]); return __builtin_bit_cast(bf16x8, w); }
; __device__ __forceinline__ void gmlp_compute(GmlpRegs& R, const Args& a, const Ctx& C, int c, int hd) {
;     ...
;     if (tid < 128) { const float mu = R.s1 * (1.0f / DA), var = R.s2 * (1.0f / DA) - mu * mu; ST[2 * tid] = mu; ST[2 * tid + 1] = __builtin_amdgcn_rsqf(var + EPS); }
;     __syncthreads();
;     const float lg = R.lg, lb = R.lb;
;     bf16x8 af[4];
; #pragma unroll
;     for (int ks = 0; ks < 4; ++ks) { f32x4 lo, hi;
; #pragma unroll
;         for (int e = 0; e < 8; ++e) { const int sl = 32 * ks + 8 * q + e;
;             const float v = __uint_as_float((unsigned)*(const LAS unsigned short*)(VL + sl * 260 + (16 * w + fr) * 2) << 16);
;             const float x = (v - ST[2 * sl]) * ST[2 * sl + 1] * lg + lb; if (e < 4) lo[e] = x; else hi[e - 4] = x; }
;         af[ks] = pack8(lo, hi); }
.LBB0_973:
	s_or_b64 exec, exec, s[4:5]
	s_waitcnt lgkmcnt(0)
	s_barrier
	v_add_u32_e32 v18, v165, v184
	ds_read_b128 v[2:5], v183
	ds_read_u16 v6, v18 offset:34816
	ds_read_u16 v7, v18 offset:35076
	ds_read_u16 v14, v18 offset:35596
	ds_read_u16 v15, v18 offset:36116
	ds_read_u16 v19, v18 offset:36636
	ds_read_u16 v20, v18 offset:43396
	ds_read_u16 v21, v18 offset:43916
	ds_read_u16 v22, v18 offset:44436
	s_waitcnt lgkmcnt(6)
	v_lshlrev_b32_e32 v11, 16, v7
	v_lshlrev_b32_e32 v10, 16, v6
	ds_read_b128 v[6:9], v168
	v_mov_b32_e32 v12, v2
	v_mov_b32_e32 v13, v4
	v_pk_add_f32 v[10:11], v[10:11], v[12:13] neg_lo:[0,1] neg_hi:[0,1]
	v_mov_b32_e32 v4, v3
	v_pk_mul_f32 v[2:3], v[4:5], v[10:11]
	s_waitcnt lgkmcnt(0)
	v_mov_b32_e32 v5, v8
	v_pk_fma_f32 v[10:11], v[98:99], v[2:3], v[100:101]
	v_add_u32_e32 v2, v165, v167
	v_lshlrev_b32_e32 v3, 16, v14
	ds_read_u16 v4, v2 offset:34816
	ds_read_u16 v14, v2 offset:35336
	ds_read_u16 v23, v2 offset:35856
	ds_read_u16 v24, v2 offset:42616
	ds_read_u16 v25, v2 offset:43136
	ds_read_u16 v113, v18 offset:61596
	s_waitcnt lgkmcnt(5)
	v_lshlrev_b32_e32 v2, 16, v4
	v_mov_b32_e32 v4, v6
	v_pk_add_f32 v[2:3], v[2:3], v[4:5] neg_lo:[0,1] neg_hi:[0,1]
	v_mov_b32_e32 v8, v7
	v_pk_mul_f32 v[6:7], v[8:9], v[2:3]
	ds_read_b128 v[2:5], v163
	v_pk_fma_f32 v[12:13], v[98:99], v[6:7], v[100:101]
	ds_read_b128 v[6:9], v166
	v_lshlrev_b32_e32 v15, 16, v15
	s_waitcnt lgkmcnt(6)
	v_lshlrev_b32_e32 v14, 16, v14
	s_waitcnt lgkmcnt(1)
	v_mov_b32_e32 v16, v2
	v_mov_b32_e32 v17, v4
	v_pk_add_f32 v[14:15], v[14:15], v[16:17] neg_lo:[0,1] neg_hi:[0,1]
	v_mov_b32_e32 v4, v3
	v_pk_mul_f32 v[2:3], v[4:5], v[14:15]
	s_waitcnt lgkmcnt(0)
	v_mov_b32_e32 v14, v6
	v_pk_fma_f32 v[4:5], v[98:99], v[2:3], v[100:101]
	v_lshlrev_b32_e32 v3, 16, v19
	v_lshlrev_b32_e32 v2, 16, v23
	v_mov_b32_e32 v15, v8
	v_pk_add_f32 v[2:3], v[2:3], v[14:15] neg_lo:[0,1] neg_hi:[0,1]
	v_mov_b32_e32 v8, v7
	v_pk_mul_f32 v[2:3], v[8:9], v[2:3]
	ds_read_b128 v[6:9], v185
	v_pk_fma_f32 v[14:15], v[98:99], v[2:3], v[100:101]
	v_cvt_pk_bf16_f32 v2, v10, v11
	v_cvt_pk_bf16_f32 v3, v12, v13
	ds_read_b128 v[10:13], v186
	v_cvt_pk_bf16_f32 v4, v4, v5
	v_cvt_pk_bf16_f32 v5, v14, v15
	v_lshlrev_b32_e32 v15, 16, v20
	v_lshlrev_b32_e32 v14, 16, v24
	s_waitcnt lgkmcnt(1)
	v_mov_b32_e32 v16, v6
	v_mov_b32_e32 v17, v8
	v_pk_add_f32 v[14:15], v[14:15], v[16:17] neg_lo:[0,1] neg_hi:[0,1]
	v_mov_b32_e32 v8, v7
	v_pk_mul_f32 v[6:7], v[8:9], v[14:15]
	s_waitcnt lgkmcnt(0)
	v_mov_b32_e32 v8, v10
	v_pk_fma_f32 v[14:15], v[98:99], v[6:7], v[100:101]
	v_lshlrev_b32_e32 v7, 16, v21
	v_lshlrev_b32_e32 v6, 16, v25
	v_mov_b32_e32 v9, v12
	v_pk_add_f32 v[16:17], v[6:7], v[8:9] neg_lo:[0,1] neg_hi:[0,1]
	ds_read_u16 v19, v187 offset:34816
	ds_read_u16 v20, v187 offset:35336
	ds_read_u16 v21, v187 offset:42096
	ds_read_b128 v[6:9], v188
	v_mov_b32_e32 v12, v11
	v_pk_mul_f32 v[10:11], v[12:13], v[16:17]
	v_lshlrev_b32_e32 v13, 16, v22
	s_waitcnt lgkmcnt(3)
	v_lshlrev_b32_e32 v12, 16, v19
	s_waitcnt lgkmcnt(0)
	v_mov_b32_e32 v16, v6
	v_mov_b32_e32 v17, v8
	v_pk_add_f32 v[12:13], v[12:13], v[16:17] neg_lo:[0,1] neg_hi:[0,1]
	v_mov_b32_e32 v8, v7
	v_pk_mul_f32 v[6:7], v[8:9], v[12:13]
	v_pk_fma_f32 v[10:11], v[98:99], v[10:11], v[100:101]
	v_pk_fma_f32 v[12:13], v[98:99], v[6:7], v[100:101]
	ds_read_b128 v[6:9], v189
	ds_read_u16 v16, v18 offset:44956
	ds_read_u16 v22, v18 offset:51716
	ds_read_u16 v23, v18 offset:52236
	ds_read_u16 v24, v18 offset:52756
	ds_read_u16 v26, v18 offset:53276
	ds_read_u16 v27, v18 offset:60036
	ds_read_u16 v28, v18 offset:60556
	ds_read_u16 v36, v18 offset:61076
	s_waitcnt lgkmcnt(7)
	v_lshlrev_b32_e32 v17, 16, v16
	v_lshlrev_b32_e32 v16, 16, v20
	v_mov_b32_e32 v18, v6
	v_mov_b32_e32 v19, v8
	v_pk_add_f32 v[16:17], v[16:17], v[18:19] neg_lo:[0,1] neg_hi:[0,1]
	v_mov_b32_e32 v8, v7
	v_pk_mul_f32 v[6:7], v[8:9], v[16:17]
	ds_read_u16 v25, v187 offset:42616
	ds_read_u16 v29, v187 offset:43136
	v_pk_fma_f32 v[16:17], v[98:99], v[6:7], v[100:101]
	v_cvt_pk_bf16_f32 v7, v10, v11
	v_cvt_pk_bf16_f32 v8, v12, v13
	ds_read_b128 v[10:13], v190
	v_cvt_pk_bf16_f32 v6, v14, v15
	v_cvt_pk_bf16_f32 v9, v16, v17
	ds_read_b128 v[14:17], v191
	s_waitcnt lgkmcnt(10)
	v_lshlrev_b32_e32 v19, 16, v22
	v_lshlrev_b32_e32 v18, 16, v21
	s_waitcnt lgkmcnt(1)
	v_mov_b32_e32 v20, v10
	v_mov_b32_e32 v21, v12
	v_pk_add_f32 v[18:19], v[18:19], v[20:21] neg_lo:[0,1] neg_hi:[0,1]
	v_mov_b32_e32 v12, v11
	v_pk_mul_f32 v[10:11], v[12:13], v[18:19]
	s_waitcnt lgkmcnt(0)
	v_mov_b32_e32 v12, v14
	v_pk_fma_f32 v[18:19], v[98:99], v[10:11], v[100:101]
	v_lshlrev_b32_e32 v11, 16, v23
	v_lshlrev_b32_e32 v10, 16, v25
	v_mov_b32_e32 v13, v16
	v_pk_add_f32 v[10:11], v[10:11], v[12:13] neg_lo:[0,1] neg_hi:[0,1]
	v_mov_b32_e32 v16, v15
	v_pk_mul_f32 v[14:15], v[16:17], v[10:11]
	ds_read_b128 v[10:13], v192
	v_pk_fma_f32 v[20:21], v[98:99], v[14:15], v[100:101]
	ds_read_b128 v[14:17], v194
	v_lshlrev_b32_e32 v23, 16, v24
	v_lshlrev_b32_e32 v22, 16, v29
	s_waitcnt lgkmcnt(1)
	v_mov_b32_e32 v24, v10
	v_mov_b32_e32 v25, v12
	v_pk_add_f32 v[22:23], v[22:23], v[24:25] neg_lo:[0,1] neg_hi:[0,1]
	v_mov_b32_e32 v12, v11
	v_pk_mul_f32 v[10:11], v[12:13], v[22:23]
	s_waitcnt lgkmcnt(0)
	v_mov_b32_e32 v22, v14
	v_pk_fma_f32 v[12:13], v[98:99], v[10:11], v[100:101]
	ds_read_u16 v10, v193 offset:34816
	ds_read_u16 v24, v193 offset:41576
	ds_read_u16 v29, v193 offset:42096
	ds_read_u16 v38, v193 offset:42616
	ds_read_u16 v121, v193 offset:43136
	v_lshlrev_b32_e32 v11, 16, v26
	s_waitcnt lgkmcnt(4)
; #define LAS __attribute__((address_space(3)))
; #define MFMA16(A, B, Cc) __builtin_amdgcn_mfma_f32_16x16x32_bf16((A), (B), (Cc), 0, 0, 0)
; #define PIN(x) asm volatile("" : "+v"(x))
; __device__ __forceinline__ float bf_lo(unsigned w) { return __uint_as_float(w << 16); }
; __device__ __forceinline__ unsigned pk4f8(float a, float b, float c, float d) { int p = __builtin_amdgcn_cvt_pk_fp8_f32(sat8(a), sat8(b), 0, false); p = __builtin_amdgcn_cvt_pk_fp8_f32(sat8(c), sat8(d), p, true); return (unsigned)p; }
; __device__ __forceinline__ float bf_hi(unsigned w) { return __uint_as_float(w & 0xffff0000u); }
; __device__ __forceinline__ bf16x8 pack8(f32x4 lo, f32x4 hi) { v4u w; w.x = pk2(lo[0], lo[1]); w.y = pk2(lo[2], lo[3]); w.z = pk2(hi[0], hi[1]); w.w = pk2(hi[2], hi[3]); return __builtin_bit_cast(bf16x8, w); }
; __device__ __forceinline__ void gmlp_compute(GmlpRegs& R, const Args& a, const Ctx& C, int c, int hd) {
;     ...
;     const float lg = R.lg, lb = R.lb;
;     bf16x8 af[4];
; #pragma unroll
;     for (int ks = 0; ks < 4; ++ks) { f32x4 lo, hi;
; #pragma unroll
;         for (int e = 0; e < 8; ++e) { const int sl = 32 * ks + 8 * q + e;
;             const float v = __uint_as_float((unsigned)*(const LAS unsigned short*)(VL + sl * 260 + (16 * w + fr) * 2) << 16);
;             const float x = (v - ST[2 * sl]) * ST[2 * sl + 1] * lg + lb; if (e < 4) lo[e] = x; else hi[e - 4] = x; }
;         af[ks] = pack8(lo, hi); }
;     f32x4 acc[8];
; #pragma unroll
;     for (int nt = 0; nt < 8; ++nt) { acc[nt] = (f32x4){0.f, 0.f, 0.f, 0.f};
; #pragma unroll
;         for (int ks = 0; ks <= nt / 2; ++ks) acc[nt] = MFMA16(af[ks], *(const LAS bf16x8*)(WL + (16 * nt + fr) * 272 + (32 * ks + 8 * q) * 2), acc[nt]); }
; #pragma unroll
;     for (int nt = 0; nt < 8; ++nt) PIN(R.uq[nt]);
; #pragma unroll
;     for (int nt = 0; nt < 8; ++nt) { const size_t row = T0 + 16 * nt + fr; const float bs = R.bsv[nt];
;         const float o0 = bf_lo(R.uq[nt].x) * (acc[nt][0] + bs), o1 = bf_hi(R.uq[nt].x) * (acc[nt][1] + bs);
;         const float o2 = bf_lo(R.uq[nt].y) * (acc[nt][2] + bs), o3 = bf_hi(R.uq[nt].y) * (acc[nt][3] + bs);
;         *(unsigned*)((unsigned char*)Y + row * DM + chs) = pk4f8(o0, o1, o2, o3); }
	v_lshlrev_b32_e32 v10, 16, v10
	v_mov_b32_e32 v23, v16
	v_pk_add_f32 v[10:11], v[10:11], v[22:23] neg_lo:[0,1] neg_hi:[0,1]
	v_mov_b32_e32 v16, v15
	v_pk_mul_f32 v[10:11], v[16:17], v[10:11]
	ds_read_b128 v[14:17], v195
	v_pk_fma_f32 v[22:23], v[98:99], v[10:11], v[100:101]
	v_cvt_pk_bf16_f32 v10, v18, v19
	v_cvt_pk_bf16_f32 v11, v20, v21
	v_cvt_pk_bf16_f32 v12, v12, v13
	v_cvt_pk_bf16_f32 v13, v22, v23
	v_lshlrev_b32_e32 v23, 16, v27
	s_waitcnt lgkmcnt(4)
	v_lshlrev_b32_e32 v22, 16, v24
	ds_read_b128 v[18:21], v196
	s_waitcnt lgkmcnt(1)
	v_mov_b32_e32 v24, v14
	v_mov_b32_e32 v25, v16
	v_pk_add_f32 v[26:27], v[22:23], v[24:25] neg_lo:[0,1] neg_hi:[0,1]
	v_mov_b32_e32 v16, v15
	v_add_u32_e32 v126, v199, v200
	v_pk_mul_f32 v[14:15], v[16:17], v[26:27]
	v_lshlrev_b32_e32 v31, 16, v28
	v_lshlrev_b32_e32 v30, 16, v29
	ds_read_b128 v[26:29], v126 offset:8704
	s_waitcnt lgkmcnt(1)
	v_mov_b32_e32 v32, v18
	v_mov_b32_e32 v33, v20
	v_pk_add_f32 v[34:35], v[30:31], v[32:33] neg_lo:[0,1] neg_hi:[0,1]
	ds_read_b128 v[30:33], v126 offset:8768
	v_mov_b32_e32 v20, v19
	s_waitcnt lgkmcnt(1)
	v_mfma_f32_16x16x32_bf16 v[26:29], v[2:5], v[26:29], 0
	v_mul_f32_e64 v34, v20, v34
	v_mul_f32_e64 v35, v21, v35
	ds_read_b128 v[18:21], v126 offset:13056
	v_lshlrev_b32_e32 v46, 16, v38
	ds_read_b128 v[38:41], v126 offset:17408
	ds_read_b128 v[42:45], v126 offset:17472
	s_waitcnt lgkmcnt(3)
	v_mfma_f32_16x16x32_bf16 v[26:29], v[6:9], v[30:33], v[26:29]
	v_fma_f32 v92, v98, v34, v100
	v_fma_f32 v93, v99, v35, v101
	v_lshlrev_b32_e32 v47, 16, v36
	ds_read_b128 v[30:33], v126 offset:13120
	ds_read_b128 v[34:37], v197
	s_waitcnt lgkmcnt(4)
	v_mfma_f32_16x16x32_bf16 v[18:21], v[2:5], v[18:21], 0
	v_fma_f32 v88, v98, v14, v100
	v_fma_f32 v89, v99, v15, v101
	ds_read_b128 v[22:25], v126
	ds_read_b128 v[14:17], v126 offset:4352
	s_waitcnt lgkmcnt(5)
	v_mfma_f32_16x16x32_bf16 v[38:41], v[2:5], v[38:41], 0
	s_lshl_b64 s[4:5], s[70:71], 11
	s_mov_b64 s[8:9], 0x2300000
	v_readlane_b32 s16, v249, 1
	s_waitcnt lgkmcnt(3)
	v_mfma_f32_16x16x32_bf16 v[18:21], v[6:9], v[30:33], v[18:21]
	ds_read_b128 v[30:33], v198
	s_waitcnt lgkmcnt(3)
	v_mov_b32_e32 v48, v34
	v_mov_b32_e32 v49, v36
	v_pk_add_f32 v[90:91], v[46:47], v[48:49] neg_lo:[0,1] neg_hi:[0,1]
	v_mov_b32_e32 v36, v35
	ds_read_b128 v[46:49], v126 offset:17536
	v_mfma_f32_16x16x32_bf16 v[38:41], v[6:9], v[42:45], v[38:41]
	v_mul_f32_e64 v42, v36, v90
	v_mul_f32_e64 v43, v37, v91
	ds_read_b128 v[34:37], v126 offset:21760
	v_pk_fma_f32 v[122:123], v[98:99], v[42:43], v[100:101]
	ds_read_b128 v[42:45], v126 offset:21824
	s_waitcnt lgkmcnt(1)
	v_mfma_f32_16x16x32_bf16 v[34:37], v[2:5], v[34:37], 0
	v_lshlrev_b32_e32 v91, 16, v113
	v_lshlrev_b32_e32 v90, 16, v121
	v_mov_b32_e32 v124, v30
	v_mfma_f32_16x16x32_bf16 v[38:41], v[10:13], v[46:49], v[38:41]
	ds_read_b128 v[46:49], v126 offset:21888
	v_mov_b32_e32 v125, v32
	v_pk_add_f32 v[90:91], v[90:91], v[124:125] neg_lo:[0,1] neg_hi:[0,1]
	s_waitcnt lgkmcnt(1)
	v_mfma_f32_16x16x32_bf16 v[34:37], v[6:9], v[42:45], v[34:37]
	ds_read_b128 v[42:45], v126 offset:26112
	v_mov_b32_e32 v32, v31
	v_readlane_b32 s17, v249, 2
	s_waitcnt lgkmcnt(1)
	v_mfma_f32_16x16x32_bf16 v[34:37], v[10:13], v[46:49], v[34:37]
	v_mul_f32_e64 v46, v32, v90
	v_mul_f32_e64 v47, v33, v91
	ds_read_b128 v[30:33], v126 offset:26176
	v_pk_fma_f32 v[98:99], v[98:99], v[46:47], v[100:101]
	s_waitcnt lgkmcnt(1)
	v_mfma_f32_16x16x32_bf16 v[42:45], v[2:5], v[42:45], 0
	v_cvt_pk_bf16_f32 v46, v88, v89
	ds_read_b128 v[88:91], v126 offset:26240
	v_cvt_pk_bf16_f32 v47, v92, v93
	s_waitcnt lgkmcnt(1)
	v_mfma_f32_16x16x32_bf16 v[30:33], v[6:9], v[30:33], v[42:45]
	v_cvt_pk_bf16_f32 v48, v122, v123
	v_cvt_pk_bf16_f32 v49, v98, v99
	v_readlane_b32 s18, v249, 3
	ds_read_b128 v[42:45], v126 offset:26304
	s_waitcnt lgkmcnt(1)
	v_mfma_f32_16x16x32_bf16 v[30:33], v[10:13], v[88:91], v[30:33]
	v_readlane_b32 s19, v249, 4
	v_readlane_b32 s20, v249, 5
	v_readlane_b32 s21, v249, 6
	s_waitcnt lgkmcnt(0)
	v_mfma_f32_16x16x32_bf16 v[30:33], v[46:49], v[42:45], v[30:33]
	ds_read_b128 v[42:45], v126 offset:30464
	ds_read_b128 v[88:91], v126 offset:30528
	v_readlane_b32 s22, v249, 7
	v_readlane_b32 s23, v249, 8
	v_mfma_f32_16x16x32_bf16 v[22:25], v[2:5], v[22:25], 0
	v_readlane_b32 s24, v249, 9
	v_readlane_b32 s25, v249, 10
	v_readlane_b32 s26, v249, 11
	v_mfma_f32_16x16x32_bf16 v[14:17], v[2:5], v[14:17], 0
	v_readlane_b32 s27, v249, 12
	v_readlane_b32 s28, v249, 13
	v_readlane_b32 s29, v249, 14
	s_waitcnt lgkmcnt(1)
	v_mfma_f32_16x16x32_bf16 v[2:5], v[2:5], v[42:45], 0
	v_readlane_b32 s30, v249, 15
	v_readlane_b32 s31, v249, 16
	s_mov_b64 s[14:15], s[22:23]
	s_waitcnt lgkmcnt(0)
	v_mfma_f32_16x16x32_bf16 v[2:5], v[6:9], v[88:91], v[2:5]
	ds_read_b128 v[6:9], v126 offset:30592
	ds_read_b128 v[42:45], v126 offset:30656
	s_waitcnt vmcnt(23)
	s_waitcnt vmcnt(22)
	s_waitcnt lgkmcnt(1)
	v_mfma_f32_16x16x32_bf16 v[2:5], v[10:13], v[6:9], v[2:5]
	v_lshlrev_b32_e32 v6, 16, v110
	v_add_f32_e32 v7, v161, v22
	v_mul_f32_e32 v6, v7, v6
	v_and_b32_e32 v7, 0xffff0000, v110
	v_add_f32_e32 v8, v161, v23
	v_mul_f32_e32 v7, v8, v7
	v_med3_f32 v6, v6, s1, v128
	v_med3_f32 v7, v7, s1, v128
	v_mov_b32_e32 v11, 0
	v_lshlrev_b32_e32 v8, 16, v111
	v_add_f32_e32 v9, v161, v24
	v_cvt_pk_fp8_f32 v11, v6, v7
	v_mul_f32_e32 v8, v9, v8
	v_and_b32_e32 v9, 0xffff0000, v111
	v_add_f32_e32 v10, v161, v25
	v_mul_f32_e32 v6, v10, v9
	v_med3_f32 v7, v8, s1, v128
	v_med3_f32 v6, v6, s1, v128
	v_cvt_pk_fp8_f32 v11, v7, v6 op_sel:[0,0,1]
	v_lshlrev_b32_e32 v8, 16, v118
	v_add_f32_e32 v9, v160, v14
	v_mul_f32_e32 v8, v9, v8
	v_and_b32_e32 v9, 0xffff0000, v118
	v_add_f32_e32 v10, v160, v15
	v_lshlrev_b64 v[6:7], 11, v[116:117]
	v_mul_f32_e32 v9, v10, v9
	v_lshl_add_u64 v[6:7], v[142:143], 0, v[6:7]
	v_med3_f32 v8, v8, s1, v128
	v_med3_f32 v9, v9, s1, v128
	v_mov_b32_e32 v13, 0
	s_waitcnt vmcnt(21)
; #define LAS __attribute__((address_space(3)))
; __device__ __forceinline__ float bf_lo(unsigned w) { return __uint_as_float(w << 16); }
; __device__ __forceinline__ unsigned pk4f8(float a, float b, float c, float d) { int p = __builtin_amdgcn_cvt_pk_fp8_f32(sat8(a), sat8(b), 0, false); p = __builtin_amdgcn_cvt_pk_fp8_f32(sat8(c), sat8(d), p, true); return (unsigned)p; }
; __device__ __forceinline__ float bf_hi(unsigned w) { return __uint_as_float(w & 0xffff0000u); }
; __device__ __forceinline__ void s5_prompt_task(const Args& a, const Ctx& C, int b, int g, v4u (&xv)[8]) {
;     const bf16* PROJ = (const bf16*)(a.ws + WS_PROJ); bf16* Y = (bf16*)(a.ws + WS_Y);
;     LAS unsigned char* XS = C.lds;
;     LAS float* SH = (LAS float*)(C.lds + 67584);
;     LAS float* TW = (LAS float*)(C.lds + 67584 + 128 * 132 * 4);
;     const int lane = C.lane, n = lane & 15, q = lane >> 4, w = C.wave;
;     const size_t row0 = (size_t)b * SEQ;
;     const bf16* XBg = (const bf16*)(a.ws + WS_XB) + ((size_t)g * MP + row0) * 16; const bf16* ZBg = (const bf16*)(a.ws + WS_ZB) + ((size_t)g * MP + row0) * 16;
;     __syncthreads();
; __device__ __forceinline__ void gmlp_compute(GmlpRegs& R, const Args& a, const Ctx& C, int c, int hd) {
;     ...
;     for (int nt = 0; nt < 8; ++nt) { const size_t row = T0 + 16 * nt + fr; const float bs = R.bsv[nt];
;         const float o0 = bf_lo(R.uq[nt].x) * (acc[nt][0] + bs), o1 = bf_hi(R.uq[nt].x) * (acc[nt][1] + bs);
;         const float o2 = bf_lo(R.uq[nt].y) * (acc[nt][2] + bs), o3 = bf_hi(R.uq[nt].y) * (acc[nt][3] + bs);
;         *(unsigned*)((unsigned char*)Y + row * DM + chs) = pk4f8(o0, o1, o2, o3); }
	s_waitcnt vmcnt(20)
	s_waitcnt vmcnt(19)
	s_waitcnt vmcnt(18)
	s_waitcnt vmcnt(17)
	s_waitcnt vmcnt(16)
	global_store_dword v[6:7], v11, off
	v_lshlrev_b32_e32 v10, 16, v119
	v_add_f32_e32 v11, v160, v16
	v_cvt_pk_fp8_f32 v13, v8, v9
	v_mul_f32_e32 v10, v11, v10
	v_and_b32_e32 v11, 0xffff0000, v119
	v_add_f32_e32 v12, v160, v17
	v_mul_f32_e32 v8, v12, v11
	v_med3_f32 v9, v10, s1, v128
	v_med3_f32 v8, v8, s1, v128
	v_cvt_pk_fp8_f32 v13, v9, v8 op_sel:[0,0,1]
	v_add_co_u32_e32 v8, vcc, s2, v6
	v_add_f32_e32 v10, v159, v27
	s_nop 0
	v_addc_co_u32_e32 v9, vcc, 0, v7, vcc
	global_store_dword v[8:9], v13, off
	v_lshlrev_b32_e32 v8, 16, v114
	v_add_f32_e32 v9, v159, v26
	v_mul_f32_e32 v8, v9, v8
	v_and_b32_e32 v9, 0xffff0000, v114
	v_mul_f32_e32 v9, v10, v9
	v_med3_f32 v8, v8, s1, v128
	v_med3_f32 v9, v9, s1, v128
	v_mov_b32_e32 v13, 0
	v_lshlrev_b32_e32 v10, 16, v115
	v_add_f32_e32 v11, v159, v28
	v_cvt_pk_fp8_f32 v13, v8, v9
	v_mul_f32_e32 v10, v11, v10
	v_and_b32_e32 v11, 0xffff0000, v115
	v_add_f32_e32 v12, v159, v29
	v_mul_f32_e32 v8, v12, v11
	v_med3_f32 v9, v10, s1, v128
	v_med3_f32 v8, v8, s1, v128
	v_cvt_pk_fp8_f32 v13, v9, v8 op_sel:[0,0,1]
	v_add_co_u32_e32 v8, vcc, s33, v6
	v_add_f32_e32 v10, v156, v19
	s_nop 0
	v_addc_co_u32_e32 v9, vcc, 0, v7, vcc
	global_store_dword v[8:9], v13, off
	v_lshlrev_b32_e32 v8, 16, v108
	v_add_f32_e32 v9, v156, v18
	v_mul_f32_e32 v8, v9, v8
	v_and_b32_e32 v9, 0xffff0000, v108
	v_mul_f32_e32 v9, v10, v9
	v_med3_f32 v8, v8, s1, v128
	v_med3_f32 v9, v9, s1, v128
	v_mov_b32_e32 v13, 0
	v_lshlrev_b32_e32 v10, 16, v109
	v_add_f32_e32 v11, v156, v20
	v_cvt_pk_fp8_f32 v13, v8, v9
	v_mul_f32_e32 v10, v11, v10
	v_and_b32_e32 v11, 0xffff0000, v109
	v_add_f32_e32 v12, v156, v21
	v_mul_f32_e32 v8, v12, v11
	v_med3_f32 v9, v10, s1, v128
	v_med3_f32 v8, v8, s1, v128
	v_cvt_pk_fp8_f32 v13, v9, v8 op_sel:[0,0,1]
	v_add_co_u32_e32 v8, vcc, s74, v6
	v_add_f32_e32 v10, v154, v39
	s_nop 0
	v_addc_co_u32_e32 v9, vcc, 0, v7, vcc
	global_store_dword v[8:9], v13, off
	v_lshlrev_b32_e32 v8, 16, v106
	v_add_f32_e32 v9, v154, v38
	v_mul_f32_e32 v8, v9, v8
	v_and_b32_e32 v9, 0xffff0000, v106
	v_mul_f32_e32 v9, v10, v9
	v_med3_f32 v8, v8, s1, v128
	v_med3_f32 v9, v9, s1, v128
	v_mov_b32_e32 v13, 0
	v_lshlrev_b32_e32 v10, 16, v107
	v_add_f32_e32 v11, v154, v40
	v_cvt_pk_fp8_f32 v13, v8, v9
	v_mul_f32_e32 v10, v11, v10
	v_and_b32_e32 v11, 0xffff0000, v107
	v_add_f32_e32 v12, v154, v41
	v_mul_f32_e32 v8, v12, v11
	v_med3_f32 v9, v10, s1, v128
	v_med3_f32 v8, v8, s1, v128
	v_cvt_pk_fp8_f32 v13, v9, v8 op_sel:[0,0,1]
	v_add_co_u32_e32 v8, vcc, s75, v6
	v_add_f32_e32 v10, v152, v35
	s_nop 0
	v_addc_co_u32_e32 v9, vcc, 0, v7, vcc
	global_store_dword v[8:9], v13, off
	v_lshlrev_b32_e32 v8, 16, v104
	v_add_f32_e32 v9, v152, v34
	v_mul_f32_e32 v8, v9, v8
	v_and_b32_e32 v9, 0xffff0000, v104
	v_mul_f32_e32 v9, v10, v9
	v_med3_f32 v8, v8, s1, v128
	v_med3_f32 v9, v9, s1, v128
	v_mov_b32_e32 v13, 0
	v_lshlrev_b32_e32 v10, 16, v105
	v_add_f32_e32 v11, v152, v36
	v_cvt_pk_fp8_f32 v13, v8, v9
	v_mul_f32_e32 v10, v11, v10
	v_and_b32_e32 v11, 0xffff0000, v105
	v_add_f32_e32 v12, v152, v37
	v_mul_f32_e32 v8, v12, v11
	v_med3_f32 v9, v10, s1, v128
	v_med3_f32 v8, v8, s1, v128
	v_cvt_pk_fp8_f32 v13, v9, v8 op_sel:[0,0,1]
	v_add_co_u32_e32 v8, vcc, s76, v6
	v_add_f32_e32 v10, v151, v31
	s_nop 0
	v_addc_co_u32_e32 v9, vcc, 0, v7, vcc
	global_store_dword v[8:9], v13, off
	v_lshlrev_b32_e32 v8, 16, v102
	v_add_f32_e32 v9, v151, v30
	v_mul_f32_e32 v8, v9, v8
	v_and_b32_e32 v9, 0xffff0000, v102
	v_mul_f32_e32 v9, v10, v9
	v_med3_f32 v8, v8, s1, v128
	v_med3_f32 v9, v9, s1, v128
	v_mov_b32_e32 v13, 0
	v_lshlrev_b32_e32 v10, 16, v103
	v_add_f32_e32 v11, v151, v32
	v_cvt_pk_fp8_f32 v13, v8, v9
	v_mul_f32_e32 v10, v11, v10
	v_and_b32_e32 v11, 0xffff0000, v103
	v_add_f32_e32 v12, v151, v33
	v_mul_f32_e32 v8, v12, v11
	v_med3_f32 v9, v10, s1, v128
	v_med3_f32 v8, v8, s1, v128
	s_waitcnt lgkmcnt(0)
	v_mfma_f32_16x16x32_bf16 v[2:5], v[46:49], v[42:45], v[2:5]
	v_cvt_pk_fp8_f32 v13, v9, v8 op_sel:[0,0,1]
	v_add_co_u32_e32 v8, vcc, s77, v6
	v_mov_b32_e32 v111, 0
	s_nop 0
	v_addc_co_u32_e32 v9, vcc, 0, v7, vcc
	global_store_dword v[8:9], v13, off
	v_lshlrev_b32_e32 v8, 16, v96
	s_nop 0
	v_add_f32_e32 v2, v150, v2
	v_mul_f32_e32 v2, v2, v8
	v_and_b32_e32 v8, 0xffff0000, v96
	v_add_f32_e32 v3, v150, v3
	v_mul_f32_e32 v3, v3, v8
	v_lshlrev_b32_e32 v8, 16, v97
	v_add_f32_e32 v4, v150, v4
	v_mul_f32_e32 v4, v4, v8
	v_and_b32_e32 v8, 0xffff0000, v97
	v_add_f32_e32 v5, v150, v5
	v_med3_f32 v2, v2, s1, v128
	v_med3_f32 v3, v3, s1, v128
	v_mov_b32_e32 v9, 0
	v_cvt_pk_fp8_f32 v9, v2, v3
	v_mul_f32_e32 v2, v5, v8
	v_med3_f32 v3, v4, s1, v128
	v_med3_f32 v2, v2, s1, v128
	s_mul_i32 s1, s0, 0x2100
	s_add_u32 s4, s1, s4
	s_addc_u32 s5, 0, s5
	s_lshl_b64 s[4:5], s[4:5], 5
	s_lshl_b32 s1, s0, 9
	s_lshl_b32 s2, s0, 12
	s_add_u32 s6, s94, s1
	v_cvt_pk_fp8_f32 v9, v3, v2 op_sel:[0,0,1]
	v_add_co_u32_e32 v2, vcc, s78, v6
	v_lshlrev_b32_e32 v110, 2, v153
	s_addc_u32 s7, s95, 0
	v_addc_co_u32_e32 v3, vcc, 0, v7, vcc
	v_lshl_add_u64 v[18:19], s[6:7], 0, v[110:111]
	s_mov_b32 s1, 0x2300000
	v_lshl_add_u64 v[20:21], v[18:19], 0, s[8:9]
	v_add_co_u32_e32 v18, vcc, s1, v18
	global_store_dword v[2:3], v9, off
	s_nop 0
	v_addc_co_u32_e32 v19, vcc, 0, v19, vcc
	s_barrier
; #define LAS __attribute__((address_space(3)))
; #define PIN(x) asm volatile("" : "+v"(x))
; __device__ __forceinline__ unsigned pk2(float lo, float hi) { return pg8::cvt_pk_bf16(lo, hi); }
; __device__ __forceinline__ bf16x8 pack8(f32x4 lo, f32x4 hi) { v4u w; w.x = pk2(lo[0], lo[1]); w.y = pk2(lo[2], lo[3]); w.z = pk2(hi[0], hi[1]); w.w = pk2(hi[2], hi[3]); return __builtin_bit_cast(bf16x8, w); }
; __device__ __forceinline__ void s5_load_consts(S5C& K, const Args& a, int g, int lane) {
;     const int fr = lane & 15, q = lane >> 4;
;     const float* ABAR = (const float*)(a.ws + WS_S5C + S5C_ABAR) + (size_t)g * 128;
;     const bf16* BBAR = (const bf16*)(a.ws + WS_S5C + S5C_BBAR) + (size_t)g * 2048;
; #pragma unroll
;     for (int j = 0; j < 4; ++j) { const f32x4 x0 = *(const f32x4*)(ABAR + 2 * (16 * j + 4 * q)), x1 = *(const f32x4*)(ABAR + 2 * (16 * j + 4 * q) + 4);
;         K.ar[j] = (f32x4){x0[0], x0[2], x1[0], x1[2]}; K.ai[j] = (f32x4){x0[1], x0[3], x1[1], x1[3]}; }
; #pragma unroll
;     for (int mt = 0; mt < 8; ++mt) K.Bf[mt] = *(const v2u*)(BBAR + (mt * 16 + fr) * 16 + 4 * q);
;     const float* cre = a.in[I_CRE] + ((size_t)g * 16 + fr) * 64; const float* cim = a.in[I_CIM] + ((size_t)g * 16 + fr) * 64;
; #pragma unroll
;     for (int j = 0; j < 4; ++j) { const f32x4 r4 = *(const f32x4*)(cre + 16 * j + 4 * q), i4 = *(const f32x4*)(cim + 16 * j + 4 * q); K.Cf[j] = pack8(r4, -i4); }
;     const float* wg = a.in[I_WGLU] + (size_t)g * 512;
;     { f32x4 v, gt;
; #pragma unroll
;       for (int e = 0; e < 4; ++e) { v[e] = wg[(4 * q + e) * 32 + fr]; gt[e] = wg[(4 * q + e) * 32 + 16 + fr]; }
;       K.Wv = (v2u){pk2(v[0], v[1]), pk2(v[2], v[3])}; K.Wg = (v2u){pk2(gt[0], gt[1]), pk2(gt[2], gt[3])}; }
;     K.dsk = *(const f32x4*)(a.in[I_DSKIP] + g * 16 + 4 * q);
;     K.bv = *(const f32x4*)(a.in[I_BGLU] + g * 32 + 4 * q); K.bg = *(const f32x4*)(a.in[I_BGLU] + g * 32 + 16 + 4 * q);
; __device__ __forceinline__ void s5_prompt_task(const Args& a, const Ctx& C, int b, int g, v4u (&xv)[8]) {
;     ...
; #pragma unroll
;     for (int i = 0; i < 8; ++i) PIN(xv[i]);
; #pragma unroll
;     for (int i = 0; i < 8; ++i) { const int idx = C.tid + 512 * i, tok = idx >> 1; *(LAS v4u*)(XS + tok * 32 + (tok >> 4) * 16 + (idx & 1) * 16) = xv[i]; }
;     S5C K; s5_load_consts(K, a, g, lane);
;     __syncthreads();
	s_waitcnt vmcnt(15)
	s_waitcnt vmcnt(14)
	s_waitcnt vmcnt(13)
	s_waitcnt vmcnt(12)
	s_waitcnt vmcnt(11)
	s_waitcnt vmcnt(10)
	s_waitcnt vmcnt(9)
	s_waitcnt vmcnt(8)
	global_load_dwordx4 v[2:5], v[20:21], off offset:16
	global_load_dwordx4 v[6:9], v[20:21], off offset:144
	global_load_dwordx4 v[10:13], v[20:21], off offset:272
	global_load_dwordx4 v[14:17], v[20:21], off offset:400
	global_load_dwordx4 v[30:33], v[18:19], off
	v_and_b32_e32 v18, 0x1fe0, v94
	v_lshrrev_b32_e32 v19, 1, v0
	v_add_u32_e32 v18, 0, v18
	v_and_b32_e32 v19, 0xf0, v19
	v_and_b32_e32 v24, 16, v94
	v_add3_u32 v18, v18, v19, v24
	ds_write_b128 v18, v[74:77]
	v_and_b32_e32 v18, 0x3fe0, v87
	v_lshrrev_b32_e32 v19, 1, v146
	v_add_u32_e32 v18, 0, v18
	v_and_b32_e32 v19, 0x1f0, v19
	v_add3_u32 v18, v18, v19, v24
	ds_write_b128 v18, v[78:81]
	v_and_b32_e32 v18, 0x7fe0, v148
	v_lshrrev_b32_e32 v19, 1, v147
	v_add_u32_e32 v18, 0, v18
	v_and_b32_e32 v19, 0x3f0, v19
	v_add3_u32 v18, v18, v19, v24
	ds_write_b128 v18, v[70:73]
	v_and_b32_e32 v18, 0x7fe0, v86
	v_lshrrev_b32_e32 v19, 1, v95
	v_add_u32_e32 v18, 0, v18
	v_and_b32_e32 v19, 0x3f0, v19
	v_add3_u32 v18, v18, v19, v24
	ds_write_b128 v18, v[66:69]
	v_and_b32_e32 v18, 0xbfe0, v85
	v_lshrrev_b32_e32 v19, 1, v120
	v_add_u32_e32 v18, 0, v18
	v_and_b32_e32 v19, 0x5f0, v19
	v_add3_u32 v18, v18, v19, v24
	ds_write_b128 v18, v[58:61]
	v_and_b32_e32 v18, 0xffe0, v84
	v_lshrrev_b32_e32 v19, 1, v157
	v_add_u32_e32 v18, 0, v18
	v_and_b32_e32 v19, 0x7f0, v19
	v_add3_u32 v18, v18, v19, v24
	ds_write_b128 v18, v[62:65]
	v_and_b32_e32 v18, 0xffe0, v83
	v_lshrrev_b32_e32 v19, 1, v158
	s_add_u32 s8, s94, s2
	v_add_u32_e32 v18, 0, v18
	v_and_b32_e32 v19, 0x7f0, v19
	s_addc_u32 s9, s95, 0
	v_lshlrev_b32_e32 v110, 1, v112
	v_add3_u32 v25, v18, v19, v24
	v_lshl_add_u64 v[18:19], s[8:9], 0, v[110:111]
	v_lshlrev_b32_e32 v22, 5, v149
	v_mov_b32_e32 v23, v111
	v_lshl_add_u64 v[18:19], v[18:19], 0, v[22:23]
	s_mov_b32 s1, 0x2320000
	v_add_co_u32_e32 v22, vcc, s1, v18
	s_mov_b64 s[8:9], 0x2320000
	s_nop 0
	v_addc_co_u32_e32 v23, vcc, 0, v19, vcc
	global_load_dwordx2 v[114:115], v[22:23], off
	v_lshl_add_u64 v[18:19], v[18:19], 0, s[8:9]
	global_load_dwordx2 v[116:117], v[18:19], off offset:512
	global_load_dwordx4 v[70:73], v[20:21], off offset:128
	v_and_b32_e32 v22, 0xffe0, v82
	v_lshrrev_b32_e32 v23, 1, v155
	global_load_dwordx4 v[74:77], v[20:21], off offset:256
	global_load_dwordx4 v[66:69], v[20:21], off offset:384
	v_add_u32_e32 v22, 0, v22
	v_and_b32_e32 v23, 0x7f0, v23
	v_add3_u32 v22, v22, v23, v24
	ds_write_b128 v25, v[50:53]
	ds_write_b128 v22, v[54:57]
	global_load_dwordx2 v[126:127], v[18:19], off offset:1024
	global_load_dwordx2 v[128:129], v[18:19], off offset:1536
	global_load_dwordx2 v[130:131], v[18:19], off offset:2048
	global_load_dwordx2 v[132:133], v[18:19], off offset:2560
	global_load_dwordx2 v[134:135], v[18:19], off offset:3072
	global_load_dwordx2 v[136:137], v[18:19], off offset:3584
	v_lshl_or_b32 v18, v149, 8, s2
	v_mov_b32_e32 v19, v111
	s_mov_b64 s[16:17], s[24:25]
	v_lshl_add_u64 v[20:21], s[14:15], 0, v[18:19]
	v_lshl_add_u64 v[18:19], s[16:17], 0, v[18:19]
	v_lshlrev_b32_e32 v78, 2, v112
	v_mov_b32_e32 v79, v111
	s_mov_b64 s[20:21], s[28:29]
	v_lshl_add_u64 v[20:21], v[20:21], 0, v[78:79]
	v_lshl_add_u64 v[18:19], v[18:19], 0, v[78:79]
	s_lshl_b32 s1, s0, 11
	global_load_dwordx4 v[58:61], v[20:21], off
	global_load_dwordx4 v[50:53], v[20:21], off offset:64
	global_load_dwordx4 v[62:65], v[18:19], off
	global_load_dwordx4 v[54:57], v[18:19], off offset:64
	global_load_dwordx4 v[42:45], v[20:21], off offset:128
	global_load_dwordx4 v[34:37], v[20:21], off offset:192
	global_load_dwordx4 v[46:49], v[18:19], off offset:128
	global_load_dwordx4 v[38:41], v[18:19], off offset:192
	s_add_u32 s8, s20, s1
	v_lshlrev_b32_e32 v18, 2, v149
	s_mov_b64 s[18:19], s[26:27]
	s_addc_u32 s9, s21, 0
	v_lshl_or_b32 v18, v145, 9, v18
	s_lshl_b32 s1, s0, 4
	s_lshl_b32 s2, s0, 6
	global_load_dword v191, v18, s[8:9]
	global_load_dword v161, v18, s[8:9] offset:64
	global_load_dword v193, v18, s[8:9] offset:128
	global_load_dword v190, v18, s[8:9] offset:192
	global_load_dword v195, v18, s[8:9] offset:256
	global_load_dword v192, v18, s[8:9] offset:320
	global_load_dword v196, v18, s[8:9] offset:384
	global_load_dword v194, v18, s[8:9] offset:448
	s_add_u32 s8, s18, s2
	s_mov_b64 s[22:23], s[30:31]
	s_addc_u32 s9, s19, 0
	s_lshl_b32 s2, s0, 7
	s_add_u32 s10, s22, s2
	s_movk_i32 s2, 0x210
	v_mul_lo_u32 v102, v144, s2
	v_add3_u32 v163, 0, v102, v153
	s_addc_u32 s11, s23, 0
	global_load_dwordx4 v[18:21], v78, s[8:9]
	global_load_dwordx4 v[22:25], v78, s[10:11]
	global_load_dwordx4 v[26:29], v78, s[10:11] offset:64
	v_readlane_b32 s36, v249, 0
	s_and_b32 s36, s36, 63
	s_lshl_b32 s36, s36, 9
	s_add_u32 s36, s36, 0x2308000
	s_add_u32 s36, s94, s36
	s_addc_u32 s37, s95, 0
	s_add_u32 s38, s36, 0x8000
	s_addc_u32 s39, s37, 0
	v_lshlrev_b32_e32 v238, 3, v162
	s_nop 1
	global_load_dwordx2 v[234:235], v238, s[36:37]
	global_load_dwordx2 v[236:237], v238, s[38:39]
	s_waitcnt lgkmcnt(0)
	s_barrier
; #define LAS __attribute__((address_space(3)))
; #define S5_UPDATE(K, hre, him, xq) do { const v2u xb_ = (xq); \
;     _Pragma("unroll") for (int j = 0; j < 4; ++j) { const f32x4 cre_ = K.ar[j] * hre[j] - K.ai[j] * him[j], cim_ = K.ar[j] * him[j] + K.ai[j] * hre[j]; \
;         hre[j] = MFMA16K16(K.Bf[2 * j], xb_, cre_); him[j] = MFMA16K16(K.Bf[2 * j + 1], xb_, cim_); } } while (0)
; __device__ __forceinline__ void s5_prompt_task(const Args& a, const Ctx& C, int b, int g, v4u (&xv)[8]) {
;     ...
;     const LAS unsigned char* xsl = XS + chunk * 528 + q * 8;
;     for (int t = 0; t < 16; ++t) { const v2u xq = *(const LAS v2u*)(xsl + t * 32); S5_UPDATE(K, hre, him, xq); }
	ds_read2_b64 v[104:107], v163 offset1:4
	s_waitcnt vmcnt(32)
	v_mov_b32_e32 v78, v30
	v_mov_b32_e32 v79, v32
	v_mov_b32_e32 v80, v2
	v_mov_b32_e32 v81, v4
	v_mul_f32_e32 v86, 0, v78
	v_mul_f32_e32 v87, 0, v79
	v_mul_f32_e32 v90, 0, v80
	v_mul_f32_e32 v91, 0, v81
	v_xor_b32_e32 v83, 0x80000000, v33
	v_xor_b32_e32 v82, 0x80000000, v31
	v_xor_b32_e32 v85, 0x80000000, v5
	v_xor_b32_e32 v84, 0x80000000, v3
	v_mov_b32_e32 v118, v3
	v_fma_f32 v82, v82, 0, v86
	v_fma_f32 v83, v83, 0, v87
	v_fma_f32 v84, v84, 0, v90
	v_fma_f32 v85, v85, 0, v91
	v_mov_b32_e32 v88, v31
	v_mov_b32_e32 v89, v33
	v_mov_b32_e32 v119, v5
	s_waitcnt vmcnt(31) lgkmcnt(0)
	v_mfma_f32_16x16x16_bf16 v[138:141], v[114:115], v[104:105], v[82:85]
	s_nop 2
	v_fma_f32 v82, v88, 0, v86
	v_fma_f32 v83, v89, 0, v87
	v_fma_f32 v84, v118, 0, v90
	v_fma_f32 v85, v119, 0, v91
	v_mov_b32_e32 v86, v6
	v_mov_b32_e32 v87, v8
	s_waitcnt vmcnt(30)
	v_mfma_f32_16x16x16_bf16 v[146:149], v[116:117], v[104:105], v[82:85]
	v_mul_f32_e64 v94, v86, 0
	v_mul_f32_e64 v95, v87, 0
	v_xor_b32_e32 v91, 0x80000000, v9
	v_xor_b32_e32 v90, 0x80000000, v7
	s_waitcnt vmcnt(29)
	v_mov_b32_e32 v82, v70
	v_mov_b32_e32 v83, v72
	v_mov_b32_e32 v120, v7
	v_mul_f32_e32 v84, 0, v82
	v_mul_f32_e32 v85, 0, v83
	v_fma_f32 v92, v90, 0, v94
	v_fma_f32 v93, v91, 0, v95
	v_xor_b32_e32 v91, 0x80000000, v73
	v_xor_b32_e32 v90, 0x80000000, v71
	v_mov_b32_e32 v121, v9
	v_fma_f32 v90, v90, 0, v84
	v_fma_f32 v91, v91, 0, v85
	v_fma_f32 v98, v120, 0, v94
	v_fma_f32 v99, v121, 0, v95
	v_mov_b32_e32 v94, v71
	v_mov_b32_e32 v95, v73
	s_waitcnt vmcnt(26)
	v_mfma_f32_16x16x16_bf16 v[150:153], v[126:127], v[104:105], v[90:93]
	v_fma_f32 v96, v94, 0, v84
	v_fma_f32 v97, v95, 0, v85
	v_mov_b32_e32 v84, v74
	v_mov_b32_e32 v85, v76
	v_mov_b32_e32 v92, v10
	v_mov_b32_e32 v93, v12
	s_waitcnt vmcnt(25)
	v_mfma_f32_16x16x16_bf16 v[154:157], v[128:129], v[104:105], v[96:99]
	v_mul_f32_e64 v100, v92, 0
	v_mul_f32_e64 v101, v93, 0
	v_mul_f32_e32 v90, 0, v84
	v_mul_f32_e32 v91, 0, v85
	v_mov_b32_e32 v122, v11
	v_xor_b32_e32 v97, 0x80000000, v13
	v_xor_b32_e32 v96, 0x80000000, v11
	v_fma_f32 v98, v96, 0, v100
	v_fma_f32 v99, v97, 0, v101
	v_xor_b32_e32 v97, 0x80000000, v77
	v_xor_b32_e32 v96, 0x80000000, v75
	v_fma_f32 v96, v96, 0, v90
	v_fma_f32 v97, v97, 0, v91
	v_mov_b32_e32 v123, v13
	v_fma_f32 v166, v122, 0, v100
	v_fma_f32 v167, v123, 0, v101
	s_waitcnt vmcnt(24)
	v_mfma_f32_16x16x16_bf16 v[168:171], v[130:131], v[104:105], v[96:99]
	v_xor_b32_e32 v143, 0x80000000, v17
	v_xor_b32_e32 v142, 0x80000000, v15
	v_mov_b32_e32 v124, v15
	v_mov_b32_e32 v98, v75
	v_mov_b32_e32 v99, v77
	v_mov_b32_e32 v96, v14
	v_mov_b32_e32 v97, v16
	v_fma_f32 v164, v98, 0, v90
	v_fma_f32 v165, v99, 0, v91
	v_mov_b32_e32 v90, v66
	v_mov_b32_e32 v91, v68
	v_mul_f32_e32 v100, 0, v96
	v_mul_f32_e32 v101, 0, v97
	v_mul_f32_e32 v108, 0, v90
	v_mul_f32_e32 v109, 0, v91
	v_fma_f32 v174, v142, 0, v100
	v_fma_f32 v175, v143, 0, v101
	v_xor_b32_e32 v143, 0x80000000, v69
	v_xor_b32_e32 v142, 0x80000000, v67
	v_mov_b32_e32 v125, v17
	v_fma_f32 v172, v142, 0, v108
	v_fma_f32 v173, v143, 0, v109
	v_fma_f32 v176, v124, 0, v100
	v_fma_f32 v177, v125, 0, v101
	v_mov_b32_e32 v100, v67
	v_mov_b32_e32 v101, v69
	s_waitcnt vmcnt(22)
	v_mfma_f32_16x16x16_bf16 v[178:181], v[134:135], v[104:105], v[172:175]
	s_add_i32 s8, 0, 0x10800
	v_add_u32_e32 v3, s8, v102
	v_lshlrev_b32_e32 v7, 5, v145
	v_fma_f32 v174, v100, 0, v108
	v_fma_f32 v175, v101, 0, v109
	v_mfma_f32_16x16x16_bf16 v[164:167], v[132:133], v[104:105], v[164:167]
	v_mul_f32_e64 v108, v88, v146
	v_mul_f32_e64 v109, v89, v147
	v_add_u32_e32 v3, v3, v7
	v_fma_f32 v182, v78, v138, -v108
	v_fma_f32 v183, v79, v139, -v109
	s_waitcnt vmcnt(21)
	v_mfma_f32_16x16x16_bf16 v[172:175], v[136:137], v[104:105], v[174:177]
	v_mul_f32_e64 v104, v118, v148
	v_mul_f32_e64 v105, v119, v149
	v_mul_f32_e32 v108, v78, v146
	v_mul_f32_e32 v109, v79, v147
	v_fma_f32 v184, v80, v140, -v104
	v_fma_f32 v185, v81, v141, -v105
	v_mul_f32_e32 v104, v80, v148
	v_mul_f32_e32 v105, v81, v149
	v_fma_f32 v138, v88, v138, v108
	v_fma_f32 v139, v89, v139, v109
	v_fma_f32 v140, v118, v140, v104
	v_fma_f32 v141, v119, v141, v105
	v_mul_f32_e32 v104, v120, v156
	v_mul_f32_e32 v105, v121, v157
	v_mul_f32_e32 v108, v94, v154
	v_mul_f32_e32 v109, v95, v155
	v_fma_f32 v148, v86, v152, -v104
	v_fma_f32 v149, v87, v153, -v105
	v_fma_f32 v146, v82, v150, -v108
	v_fma_f32 v147, v83, v151, -v109
	v_mul_f32_e32 v104, v86, v156
	v_mul_f32_e32 v105, v87, v157
	v_mul_f32_e32 v108, v82, v154
	v_mul_f32_e32 v109, v83, v155
	v_fma_f32 v152, v120, v152, v104
	v_fma_f32 v153, v121, v153, v105
	v_fma_f32 v150, v94, v150, v108
	v_fma_f32 v151, v95, v151, v109
	v_mul_f32_e32 v104, v122, v166
	v_mul_f32_e32 v105, v123, v167
	v_mul_f32_e32 v108, v98, v164
	v_mul_f32_e32 v109, v99, v165
	v_fma_f32 v156, v92, v170, -v104
	v_fma_f32 v157, v93, v171, -v105
	v_fma_f32 v154, v84, v168, -v108
	v_fma_f32 v155, v85, v169, -v109
	v_mul_f32_e32 v104, v92, v166
	v_mul_f32_e32 v105, v93, v167
	v_mul_f32_e32 v108, v84, v164
	v_mul_f32_e32 v109, v85, v165
	v_fma_f32 v166, v122, v170, v104
	v_fma_f32 v167, v123, v171, v105
	v_fma_f32 v164, v98, v168, v108
	v_fma_f32 v165, v99, v169, v109
	v_mul_f32_e32 v104, v124, v174
	v_mul_f32_e32 v105, v125, v175
	v_mul_f32_e32 v108, v100, v172
	v_mul_f32_e32 v109, v101, v173
	v_fma_f32 v170, v96, v180, -v104
	v_fma_f32 v171, v97, v181, -v105
	v_fma_f32 v168, v90, v178, -v108
	v_fma_f32 v169, v91, v179, -v109
	v_mul_f32_e32 v104, v96, v174
	v_mul_f32_e32 v105, v97, v175
	v_mul_f32_e32 v108, v90, v172
	v_mul_f32_e32 v109, v91, v173
	v_mfma_f32_16x16x16_bf16 v[138:141], v[116:117], v[106:107], v[138:141]
	v_fma_f32 v174, v124, v180, v104
	v_fma_f32 v175, v125, v181, v105
	v_fma_f32 v172, v100, v178, v108
	v_fma_f32 v173, v101, v179, v109
	s_add_u32 s4, s94, s4
	v_mfma_f32_16x16x16_bf16 v[182:185], v[114:115], v[106:107], v[182:185]
	s_addc_u32 s5, s95, s5
	s_nop 1
	v_mul_f32_e32 v108, v118, v140
	v_mul_f32_e32 v109, v119, v141
	v_mul_f32_e32 v142, v88, v138
	v_mul_f32_e32 v143, v89, v139
	v_mfma_f32_16x16x16_bf16 v[146:149], v[126:127], v[106:107], v[146:149]
	v_mul_f32_e64 v138, v78, v138
	v_mul_f32_e64 v139, v79, v139
	v_fma_f32 v178, v80, v184, -v108
	v_fma_f32 v179, v81, v185, -v109
	v_fma_f32 v176, v78, v182, -v142
	v_fma_f32 v177, v79, v183, -v143
	v_mfma_f32_16x16x16_bf16 v[150:153], v[128:129], v[106:107], v[150:153]
	v_mul_f32_e64 v108, v80, v140
	v_mul_f32_e64 v109, v81, v141
	v_lshlrev_b32_e32 v7, 4, v144
	s_mov_b32 s2, 0x2308000
	v_mfma_f32_16x16x16_bf16 v[154:157], v[130:131], v[106:107], v[154:157]
	v_mov_b32_e32 v160, v111
	v_mfma_f32_16x16x16_bf16 v[164:167], v[132:133], v[106:107], v[164:167]
	v_mfma_f32_16x16x16_bf16 v[168:171], v[134:135], v[106:107], v[168:171]
	v_mfma_f32_16x16x16_bf16 v[104:107], v[136:137], v[106:107], v[172:175]
	s_nop 2
	ds_read2_b64 v[172:175], v163 offset0:8 offset1:12
	s_waitcnt lgkmcnt(0)
; #define LAS __attribute__((address_space(3)))
; #define S5_UPDATE(K, hre, him, xq) do { const v2u xb_ = (xq); \
;     _Pragma("unroll") for (int j = 0; j < 4; ++j) { const f32x4 cre_ = K.ar[j] * hre[j] - K.ai[j] * him[j], cim_ = K.ar[j] * him[j] + K.ai[j] * hre[j]; \
;         hre[j] = MFMA16K16(K.Bf[2 * j], xb_, cre_); him[j] = MFMA16K16(K.Bf[2 * j + 1], xb_, cim_); } } while (0)
; __device__ __forceinline__ void s5_prompt_task(const Args& a, const Ctx& C, int b, int g, v4u (&xv)[8]) {
;     ...
;     for (int t = 0; t < 16; ++t) { const v2u xq = *(const LAS v2u*)(xsl + t * 32); S5_UPDATE(K, hre, him, xq); }
	v_mfma_f32_16x16x16_bf16 v[140:143], v[114:115], v[172:173], v[176:179]
	s_nop 2
	v_fma_f32 v178, v118, v184, v108
	v_fma_f32 v179, v119, v185, v109
	v_fma_f32 v176, v88, v182, v138
	v_fma_f32 v177, v89, v183, v139
	v_mul_f32_e32 v108, v120, v152
	v_mul_f32_e32 v109, v121, v153
	v_mul_f32_e32 v138, v94, v150
	v_mul_f32_e32 v139, v95, v151
	v_fma_f32 v182, v86, v148, -v108
	v_fma_f32 v183, v87, v149, -v109
	v_fma_f32 v180, v82, v146, -v138
	v_fma_f32 v181, v83, v147, -v139
	v_mul_f32_e32 v108, v86, v152
	v_mul_f32_e32 v109, v87, v153
	v_mul_f32_e32 v138, v82, v150
	v_mul_f32_e32 v139, v83, v151
	v_mfma_f32_16x16x16_bf16 v[176:179], v[116:117], v[172:173], v[176:179]
	v_fma_f32 v148, v120, v148, v108
	v_fma_f32 v149, v121, v149, v109
	v_fma_f32 v146, v94, v146, v138
	v_fma_f32 v147, v95, v147, v139
	v_mul_f32_e32 v108, v122, v166
	v_mul_f32_e32 v109, v123, v167
	v_mul_f32_e32 v138, v98, v164
	v_mul_f32_e32 v139, v99, v165
	v_fma_f32 v152, v92, v156, -v108
	v_fma_f32 v153, v93, v157, -v109
	v_fma_f32 v150, v84, v154, -v138
	v_fma_f32 v151, v85, v155, -v139
	v_mul_f32_e32 v108, v92, v166
	v_mul_f32_e32 v109, v93, v167
	v_mul_f32_e32 v138, v84, v164
	v_mul_f32_e32 v139, v85, v165
	v_fma_f32 v156, v122, v156, v108
	v_fma_f32 v157, v123, v157, v109
	v_fma_f32 v154, v98, v154, v138
	v_fma_f32 v155, v99, v155, v139
	v_mul_f32_e32 v108, v124, v106
	v_mul_f32_e32 v109, v125, v107
	v_mul_f32_e32 v138, v100, v104
	v_mul_f32_e32 v139, v101, v105
	v_mfma_f32_16x16x16_bf16 v[146:149], v[128:129], v[172:173], v[146:149]
	v_fma_f32 v166, v96, v170, -v108
	v_fma_f32 v167, v97, v171, -v109
	v_fma_f32 v164, v90, v168, -v138
	v_fma_f32 v165, v91, v169, -v139
	v_mul_f32_e32 v138, v96, v106
	v_mul_f32_e32 v139, v97, v107
	v_mul_f32_e32 v104, v90, v104
	v_mul_f32_e32 v105, v91, v105
	v_mfma_f32_16x16x16_bf16 v[180:183], v[126:127], v[172:173], v[180:183]
	v_mfma_f32_16x16x16_bf16 v[106:109], v[134:135], v[172:173], v[164:167]
	s_nop 2
	v_fma_f32 v166, v124, v170, v138
	v_fma_f32 v167, v125, v171, v139
	v_fma_f32 v164, v100, v168, v104
	v_fma_f32 v165, v101, v169, v105
	v_mul_f32_e32 v104, v118, v178
	v_mul_f32_e32 v105, v119, v179
	v_mul_f32_e32 v138, v88, v176
	v_mul_f32_e32 v139, v89, v177
	v_mfma_f32_16x16x16_bf16 v[154:157], v[132:133], v[172:173], v[154:157]
	v_fma_f32 v170, v80, v142, -v104
	v_fma_f32 v171, v81, v143, -v105
	v_fma_f32 v168, v78, v140, -v138
	v_fma_f32 v169, v79, v141, -v139
	v_mul_f32_e32 v104, v80, v178
	v_mul_f32_e32 v105, v81, v179
	v_mul_f32_e32 v138, v78, v176
	v_mul_f32_e32 v139, v79, v177
	v_mfma_f32_16x16x16_bf16 v[150:153], v[130:131], v[172:173], v[150:153]
	v_fma_f32 v142, v118, v142, v104
	v_fma_f32 v143, v119, v143, v105
	v_fma_f32 v140, v88, v140, v138
	v_fma_f32 v141, v89, v141, v139
	v_mul_f32_e32 v104, v120, v148
	v_mul_f32_e32 v105, v121, v149
	v_mfma_f32_16x16x16_bf16 v[164:167], v[136:137], v[172:173], v[164:167]
	v_fma_f32 v178, v86, v182, -v104
	v_fma_f32 v179, v87, v183, -v105
	v_mul_f32_e32 v104, v86, v148
	v_mul_f32_e32 v105, v87, v149
	v_mfma_f32_16x16x16_bf16 v[138:141], v[116:117], v[174:175], v[140:143]
	v_fma_f32 v148, v120, v182, v104
	v_fma_f32 v149, v121, v183, v105
	v_mul_f32_e32 v104, v122, v156
	v_mul_f32_e32 v105, v123, v157
	v_mul_f32_e32 v142, v94, v146
	v_mul_f32_e32 v143, v95, v147
	v_fma_f32 v182, v92, v152, -v104
	v_fma_f32 v183, v93, v153, -v105
	v_fma_f32 v176, v82, v180, -v142
	v_fma_f32 v177, v83, v181, -v143
	v_mul_f32_e32 v142, v82, v146
	v_mul_f32_e32 v143, v83, v147
	v_mul_f32_e32 v104, v92, v156
	v_mul_f32_e32 v105, v93, v157
	v_fma_f32 v146, v94, v180, v142
	v_fma_f32 v147, v95, v181, v143
	v_mul_f32_e32 v142, v98, v154
	v_mul_f32_e32 v143, v99, v155
	v_mfma_f32_16x16x16_bf16 v[168:171], v[114:115], v[174:175], v[168:171]
	v_fma_f32 v180, v84, v150, -v142
	v_fma_f32 v181, v85, v151, -v143
	v_mul_f32_e32 v142, v84, v154
	v_mul_f32_e32 v143, v85, v155
	v_fma_f32 v152, v122, v152, v104
	v_fma_f32 v153, v123, v153, v105
	v_fma_f32 v150, v98, v150, v142
	v_fma_f32 v151, v99, v151, v143
	v_mul_f32_e32 v104, v124, v166
	v_mul_f32_e32 v105, v125, v167
	v_mul_f32_e32 v142, v100, v164
	v_mul_f32_e32 v143, v101, v165
	v_mfma_f32_16x16x16_bf16 v[146:149], v[128:129], v[174:175], v[146:149]
	v_mfma_f32_16x16x16_bf16 v[156:159], v[130:131], v[174:175], v[180:183]
	s_nop 2
	v_fma_f32 v182, v96, v108, -v104
	v_fma_f32 v183, v97, v109, -v105
	v_fma_f32 v180, v90, v106, -v142
	v_fma_f32 v181, v91, v107, -v143
	v_mul_f32_e32 v104, v96, v166
	v_mul_f32_e32 v105, v97, v167
	v_mul_f32_e32 v142, v90, v164
	v_mul_f32_e32 v143, v91, v165
	ds_read2_b64 v[164:167], v163 offset0:16 offset1:20
	v_mfma_f32_16x16x16_bf16 v[176:179], v[126:127], v[174:175], v[176:179]
	v_fma_f32 v108, v124, v108, v104
	v_fma_f32 v109, v125, v109, v105
	v_fma_f32 v106, v100, v106, v142
	v_fma_f32 v107, v101, v107, v143
	v_mul_f32_e32 v142, v88, v138
	v_mul_f32_e32 v143, v89, v139
	v_mfma_f32_16x16x16_bf16 v[150:153], v[132:133], v[174:175], v[150:153]
	v_mul_f32_e64 v138, v78, v138
	v_mul_f32_e64 v139, v79, v139
	v_fma_f32 v172, v78, v168, -v142
	v_fma_f32 v173, v79, v169, -v143
	v_fma_f32 v168, v88, v168, v138
	v_fma_f32 v169, v89, v169, v139
	v_mfma_f32_16x16x16_bf16 v[104:107], v[136:137], v[174:175], v[106:109]
	v_mul_f32_e64 v138, v94, v146
	v_mul_f32_e64 v139, v95, v147
	s_nop 0
	v_mul_f32_e32 v108, v118, v140
	v_mul_f32_e32 v109, v119, v141
	v_mfma_f32_16x16x16_bf16 v[180:183], v[134:135], v[174:175], v[180:183]
	v_fma_f32 v174, v80, v170, -v108
	v_fma_f32 v175, v81, v171, -v109
	v_mul_f32_e32 v108, v80, v140
	v_mul_f32_e32 v109, v81, v141
	s_nop 0
	v_fma_f32 v170, v118, v170, v108
	v_fma_f32 v171, v119, v171, v109
	v_mul_f32_e32 v108, v120, v148
	v_mul_f32_e32 v109, v121, v149
	s_waitcnt lgkmcnt(0)
; #define LAS __attribute__((address_space(3)))
; #define S5_UPDATE(K, hre, him, xq) do { const v2u xb_ = (xq); \
;     _Pragma("unroll") for (int j = 0; j < 4; ++j) { const f32x4 cre_ = K.ar[j] * hre[j] - K.ai[j] * him[j], cim_ = K.ar[j] * him[j] + K.ai[j] * hre[j]; \
;         hre[j] = MFMA16K16(K.Bf[2 * j], xb_, cre_); him[j] = MFMA16K16(K.Bf[2 * j + 1], xb_, cim_); } } while (0)
; __device__ __forceinline__ void s5_prompt_task(const Args& a, const Ctx& C, int b, int g, v4u (&xv)[8]) {
;     ...
;     for (int t = 0; t < 16; ++t) { const v2u xq = *(const LAS v2u*)(xsl + t * 32); S5_UPDATE(K, hre, him, xq); }
	v_mfma_f32_16x16x16_bf16 v[140:143], v[114:115], v[164:165], v[172:175]
	s_nop 2
	v_fma_f32 v174, v86, v178, -v108
	v_fma_f32 v175, v87, v179, -v109
	v_fma_f32 v172, v82, v176, -v138
	v_fma_f32 v173, v83, v177, -v139
	v_mul_f32_e32 v108, v86, v148
	v_mul_f32_e32 v109, v87, v149
	v_mul_f32_e32 v138, v82, v146
	v_mul_f32_e32 v139, v83, v147
	v_mfma_f32_16x16x16_bf16 v[168:171], v[116:117], v[164:165], v[168:171]
	v_fma_f32 v148, v120, v178, v108
	v_fma_f32 v149, v121, v179, v109
	v_fma_f32 v146, v94, v176, v138
	v_fma_f32 v147, v95, v177, v139
	v_mul_f32_e32 v108, v122, v152
	v_mul_f32_e32 v109, v123, v153
	v_mul_f32_e32 v138, v98, v150
	v_mul_f32_e32 v139, v99, v151
	v_fma_f32 v178, v92, v158, -v108
	v_fma_f32 v179, v93, v159, -v109
	v_fma_f32 v176, v84, v156, -v138
	v_fma_f32 v177, v85, v157, -v139
	v_mul_f32_e32 v108, v92, v152
	v_mul_f32_e32 v109, v93, v153
	v_mul_f32_e32 v138, v84, v150
	v_mul_f32_e32 v139, v85, v151
	v_fma_f32 v158, v122, v158, v108
	v_fma_f32 v159, v123, v159, v109
	v_fma_f32 v156, v98, v156, v138
	v_fma_f32 v157, v99, v157, v139
	v_mul_f32_e32 v108, v124, v106
	v_mul_f32_e32 v109, v125, v107
	v_mul_f32_e32 v138, v100, v104
	v_mul_f32_e32 v139, v101, v105
	v_mfma_f32_16x16x16_bf16 v[146:149], v[128:129], v[164:165], v[146:149]
	v_mul_f32_e64 v104, v90, v104
	v_mul_f32_e64 v105, v91, v105
	v_mfma_f32_16x16x16_bf16 v[152:155], v[130:131], v[164:165], v[176:179]
	s_nop 2
	v_fma_f32 v178, v96, v182, -v108
	v_fma_f32 v179, v97, v183, -v109
	v_fma_f32 v176, v90, v180, -v138
	v_fma_f32 v177, v91, v181, -v139
	v_mul_f32_e32 v138, v96, v106
	v_mul_f32_e32 v139, v97, v107
	v_mfma_f32_16x16x16_bf16 v[172:175], v[126:127], v[164:165], v[172:175]
	v_mfma_f32_16x16x16_bf16 v[106:109], v[134:135], v[164:165], v[176:179]
	s_nop 2
	v_fma_f32 v178, v124, v182, v138
	v_fma_f32 v179, v125, v183, v139
	v_fma_f32 v176, v100, v180, v104
	v_fma_f32 v177, v101, v181, v105
	v_mul_f32_e32 v104, v118, v170
	v_mul_f32_e32 v105, v119, v171
	v_mul_f32_e32 v138, v88, v168
	v_mul_f32_e32 v139, v89, v169
	v_mfma_f32_16x16x16_bf16 v[156:159], v[132:133], v[164:165], v[156:159]
	v_fma_f32 v182, v80, v142, -v104
	v_fma_f32 v183, v81, v143, -v105
	v_fma_f32 v180, v78, v140, -v138
	v_fma_f32 v181, v79, v141, -v139
	v_mul_f32_e32 v104, v80, v170
	v_mul_f32_e32 v105, v81, v171
	v_mul_f32_e32 v138, v78, v168
	v_mul_f32_e32 v139, v79, v169
	v_fma_f32 v142, v118, v142, v104
	v_fma_f32 v143, v119, v143, v105
	v_fma_f32 v140, v88, v140, v138
	v_fma_f32 v141, v89, v141, v139
	v_mfma_f32_16x16x16_bf16 v[176:179], v[136:137], v[164:165], v[176:179]
	v_mul_f32_e64 v104, v120, v148
	v_mul_f32_e64 v105, v121, v149
	v_fma_f32 v170, v86, v174, -v104
	v_fma_f32 v171, v87, v175, -v105
	v_mfma_f32_16x16x16_bf16 v[138:141], v[116:117], v[166:167], v[140:143]
	v_mul_f32_e64 v104, v86, v148
	v_mul_f32_e64 v105, v87, v149
	s_nop 0
	v_mul_f32_e32 v142, v94, v146
	v_mul_f32_e32 v143, v95, v147
	v_mfma_f32_16x16x16_bf16 v[180:183], v[114:115], v[166:167], v[180:183]
	v_fma_f32 v168, v82, v172, -v142
	v_fma_f32 v169, v83, v173, -v143
	v_mul_f32_e32 v142, v82, v146
	v_mul_f32_e32 v143, v83, v147
	s_nop 0
	v_mfma_f32_16x16x16_bf16 v[148:151], v[126:127], v[166:167], v[168:171]
	s_nop 2
	v_fma_f32 v170, v120, v174, v104
	v_fma_f32 v171, v121, v175, v105
	v_fma_f32 v168, v94, v172, v142
	v_fma_f32 v169, v95, v173, v143
	v_mul_f32_e32 v104, v122, v158
	v_mul_f32_e32 v105, v123, v159
	v_mul_f32_e32 v142, v98, v156
	v_mul_f32_e32 v143, v99, v157
	v_fma_f32 v174, v92, v154, -v104
	v_fma_f32 v175, v93, v155, -v105
	v_fma_f32 v172, v84, v152, -v142
	v_fma_f32 v173, v85, v153, -v143
	v_mul_f32_e32 v104, v92, v158
	v_mul_f32_e32 v105, v93, v159
	v_mul_f32_e32 v142, v84, v156
	v_mul_f32_e32 v143, v85, v157
	v_fma_f32 v154, v122, v154, v104
	v_fma_f32 v155, v123, v155, v105
	v_fma_f32 v152, v98, v152, v142
	v_fma_f32 v153, v99, v153, v143
	v_mul_f32_e32 v104, v124, v178
	v_mul_f32_e32 v105, v125, v179
	v_mul_f32_e32 v142, v100, v176
	v_mul_f32_e32 v143, v101, v177
	v_fma_f32 v158, v96, v108, -v104
	v_fma_f32 v159, v97, v109, -v105
	v_fma_f32 v156, v90, v106, -v142
	v_fma_f32 v157, v91, v107, -v143
	v_mul_f32_e32 v104, v96, v178
	v_mul_f32_e32 v105, v97, v179
	v_mul_f32_e32 v142, v90, v176
	v_mul_f32_e32 v143, v91, v177
	v_fma_f32 v108, v124, v108, v104
	v_fma_f32 v109, v125, v109, v105
	v_fma_f32 v106, v100, v106, v142
	v_fma_f32 v107, v101, v107, v143
	v_mfma_f32_16x16x16_bf16 v[168:171], v[128:129], v[166:167], v[168:171]
	v_mul_f32_e64 v142, v88, v138
	v_mul_f32_e64 v143, v89, v139
	v_mul_f32_e32 v138, v78, v138
	v_mul_f32_e32 v139, v79, v139
	v_fma_f32 v176, v78, v180, -v142
	v_fma_f32 v177, v79, v181, -v143
	v_mfma_f32_16x16x16_bf16 v[172:175], v[130:131], v[166:167], v[172:175]
	v_mfma_f32_16x16x16_bf16 v[152:155], v[132:133], v[166:167], v[152:155]
	v_mfma_f32_16x16x16_bf16 v[156:159], v[134:135], v[166:167], v[156:159]
	v_mfma_f32_16x16x16_bf16 v[104:107], v[136:137], v[166:167], v[106:109]
	ds_read2_b64 v[164:167], v163 offset0:24 offset1:28
	s_nop 1
	v_mul_f32_e32 v108, v118, v140
	v_mul_f32_e32 v109, v119, v141
	s_nop 0
	v_fma_f32 v178, v80, v182, -v108
	v_fma_f32 v179, v81, v183, -v109
	v_mul_f32_e32 v108, v80, v140
	v_mul_f32_e32 v109, v81, v141
	s_waitcnt lgkmcnt(0)
; #define LAS __attribute__((address_space(3)))
; #define S5_UPDATE(K, hre, him, xq) do { const v2u xb_ = (xq); \
;     _Pragma("unroll") for (int j = 0; j < 4; ++j) { const f32x4 cre_ = K.ar[j] * hre[j] - K.ai[j] * him[j], cim_ = K.ar[j] * him[j] + K.ai[j] * hre[j]; \
;         hre[j] = MFMA16K16(K.Bf[2 * j], xb_, cre_); him[j] = MFMA16K16(K.Bf[2 * j + 1], xb_, cim_); } } while (0)
; __device__ __forceinline__ void s5_prompt_task(const Args& a, const Ctx& C, int b, int g, v4u (&xv)[8]) {
;     ...
;     for (int t = 0; t < 16; ++t) { const v2u xq = *(const LAS v2u*)(xsl + t * 32); S5_UPDATE(K, hre, him, xq); }
	v_mfma_f32_16x16x16_bf16 v[140:143], v[114:115], v[164:165], v[176:179]
	s_nop 2
	v_fma_f32 v176, v88, v180, v138
	v_fma_f32 v177, v89, v181, v139
	v_mul_f32_e32 v138, v94, v168
	v_mul_f32_e32 v139, v95, v169
	v_fma_f32 v178, v118, v182, v108
	v_fma_f32 v179, v119, v183, v109
	v_mul_f32_e32 v108, v120, v170
	v_mul_f32_e32 v109, v121, v171
	v_fma_f32 v180, v82, v148, -v138
	v_fma_f32 v181, v83, v149, -v139
	v_mul_f32_e32 v138, v82, v168
	v_mul_f32_e32 v139, v83, v169
	v_mfma_f32_16x16x16_bf16 v[176:179], v[116:117], v[164:165], v[176:179]
	v_fma_f32 v182, v86, v150, -v108
	v_fma_f32 v183, v87, v151, -v109
	v_mul_f32_e32 v108, v86, v170
	v_mul_f32_e32 v109, v87, v171
	v_fma_f32 v148, v94, v148, v138
	v_fma_f32 v149, v95, v149, v139
	v_mul_f32_e32 v138, v98, v152
	v_mul_f32_e32 v139, v99, v153
	v_fma_f32 v150, v120, v150, v108
	v_fma_f32 v151, v121, v151, v109
	v_mul_f32_e32 v108, v122, v154
	v_mul_f32_e32 v109, v123, v155
	v_fma_f32 v168, v84, v172, -v138
	v_fma_f32 v169, v85, v173, -v139
	v_mul_f32_e32 v138, v84, v152
	v_mul_f32_e32 v139, v85, v153
	v_mfma_f32_16x16x16_bf16 v[146:149], v[128:129], v[164:165], v[148:151]
	v_fma_f32 v170, v92, v174, -v108
	v_fma_f32 v171, v93, v175, -v109
	v_mul_f32_e32 v108, v92, v154
	v_mul_f32_e32 v109, v93, v155
	v_fma_f32 v150, v98, v172, v138
	v_fma_f32 v151, v99, v173, v139
	v_mul_f32_e32 v138, v100, v104
	v_mul_f32_e32 v139, v101, v105
	v_fma_f32 v152, v122, v174, v108
	v_fma_f32 v153, v123, v175, v109
	v_mul_f32_e32 v108, v124, v106
	v_mul_f32_e32 v109, v125, v107
	v_fma_f32 v172, v90, v156, -v138
	v_fma_f32 v173, v91, v157, -v139
	v_mul_f32_e32 v138, v96, v106
	v_mul_f32_e32 v139, v97, v107
	v_mul_f32_e32 v104, v90, v104
	v_mul_f32_e32 v105, v91, v105
	v_mfma_f32_16x16x16_bf16 v[180:183], v[126:127], v[164:165], v[180:183]
	v_fma_f32 v174, v96, v158, -v108
	v_fma_f32 v175, v97, v159, -v109
	v_fma_f32 v158, v124, v158, v138
	v_fma_f32 v159, v125, v159, v139
	v_fma_f32 v156, v100, v156, v104
	v_fma_f32 v157, v101, v157, v105
	v_mul_f32_e32 v104, v118, v178
	v_mul_f32_e32 v105, v119, v179
	v_mul_f32_e32 v138, v88, v176
	v_mul_f32_e32 v139, v89, v177
	v_mfma_f32_16x16x16_bf16 v[150:153], v[132:133], v[164:165], v[150:153]
	v_mfma_f32_16x16x16_bf16 v[106:109], v[134:135], v[164:165], v[172:175]
	s_nop 2
	v_fma_f32 v174, v80, v142, -v104
	v_fma_f32 v175, v81, v143, -v105
	v_fma_f32 v172, v78, v140, -v138
	v_fma_f32 v173, v79, v141, -v139
	v_mul_f32_e32 v104, v80, v178
	v_mul_f32_e32 v105, v81, v179
	v_mul_f32_e32 v138, v78, v176
	v_mul_f32_e32 v139, v79, v177
	v_mfma_f32_16x16x16_bf16 v[168:171], v[130:131], v[164:165], v[168:171]
	v_fma_f32 v142, v118, v142, v104
	v_fma_f32 v143, v119, v143, v105
	v_fma_f32 v140, v88, v140, v138
	v_fma_f32 v141, v89, v141, v139
	v_mul_f32_e32 v104, v120, v148
	v_mul_f32_e32 v105, v121, v149
	v_mfma_f32_16x16x16_bf16 v[154:157], v[136:137], v[164:165], v[156:159]
	v_fma_f32 v178, v86, v182, -v104
	v_fma_f32 v179, v87, v183, -v105
	v_mul_f32_e32 v104, v86, v148
	v_mul_f32_e32 v105, v87, v149
	v_mfma_f32_16x16x16_bf16 v[138:141], v[116:117], v[166:167], v[140:143]
	v_fma_f32 v148, v120, v182, v104
	v_fma_f32 v149, v121, v183, v105
	v_mul_f32_e32 v104, v122, v152
	v_mul_f32_e32 v105, v123, v153
	v_mul_f32_e32 v142, v94, v146
	v_mul_f32_e32 v143, v95, v147
	v_fma_f32 v182, v92, v170, -v104
	v_fma_f32 v183, v93, v171, -v105
	v_fma_f32 v176, v82, v180, -v142
	v_fma_f32 v177, v83, v181, -v143
	v_mul_f32_e32 v142, v82, v146
	v_mul_f32_e32 v143, v83, v147
	v_mul_f32_e32 v104, v92, v152
	v_mul_f32_e32 v105, v93, v153
	v_fma_f32 v146, v94, v180, v142
	v_fma_f32 v147, v95, v181, v143
	v_mul_f32_e32 v142, v98, v150
	v_mul_f32_e32 v143, v99, v151
	v_fma_f32 v152, v122, v170, v104
	v_fma_f32 v153, v123, v171, v105
	v_fma_f32 v180, v84, v168, -v142
	v_fma_f32 v181, v85, v169, -v143
	v_mul_f32_e32 v142, v84, v150
	v_mul_f32_e32 v143, v85, v151
	v_mul_f32_e32 v104, v124, v156
	v_mul_f32_e32 v105, v125, v157
	v_fma_f32 v150, v98, v168, v142
	v_fma_f32 v151, v99, v169, v143
	v_mul_f32_e32 v142, v100, v154
	v_mul_f32_e32 v143, v101, v155
	v_fma_f32 v170, v96, v108, -v104
	v_fma_f32 v171, v97, v109, -v105
	v_fma_f32 v168, v90, v106, -v142
	v_fma_f32 v169, v91, v107, -v143
	v_mul_f32_e32 v104, v96, v156
	v_mul_f32_e32 v105, v97, v157
	v_mul_f32_e32 v142, v90, v154
	v_mul_f32_e32 v143, v91, v155
	v_fma_f32 v108, v124, v108, v104
	v_fma_f32 v109, v125, v109, v105
	v_fma_f32 v106, v100, v106, v142
	v_fma_f32 v107, v101, v107, v143
	v_mfma_f32_16x16x16_bf16 v[172:175], v[114:115], v[166:167], v[172:175]
	v_mul_f32_e64 v142, v88, v138
	v_mul_f32_e64 v143, v89, v139
	v_mul_f32_e32 v138, v78, v138
	v_mul_f32_e32 v139, v79, v139
	v_mfma_f32_16x16x16_bf16 v[176:179], v[126:127], v[166:167], v[176:179]
	v_mfma_f32_16x16x16_bf16 v[146:149], v[128:129], v[166:167], v[146:149]
	v_mfma_f32_16x16x16_bf16 v[180:183], v[130:131], v[166:167], v[180:183]
	v_mfma_f32_16x16x16_bf16 v[150:153], v[132:133], v[166:167], v[150:153]
	v_mfma_f32_16x16x16_bf16 v[156:159], v[134:135], v[166:167], v[168:171]
	v_mfma_f32_16x16x16_bf16 v[104:107], v[136:137], v[166:167], v[106:109]
	ds_read2_b64 v[164:167], v163 offset0:32 offset1:36
	s_nop 0
	v_fma_f32 v168, v78, v172, -v142
	v_fma_f32 v169, v79, v173, -v143
	v_mul_f32_e32 v108, v118, v140
	v_mul_f32_e32 v109, v119, v141
	s_nop 0
	v_fma_f32 v170, v80, v174, -v108
	v_fma_f32 v171, v81, v175, -v109
	v_mul_f32_e32 v108, v80, v140
	v_mul_f32_e32 v109, v81, v141
	s_waitcnt lgkmcnt(0)
; #define LAS __attribute__((address_space(3)))
; #define S5_UPDATE(K, hre, him, xq) do { const v2u xb_ = (xq); \
;     _Pragma("unroll") for (int j = 0; j < 4; ++j) { const f32x4 cre_ = K.ar[j] * hre[j] - K.ai[j] * him[j], cim_ = K.ar[j] * him[j] + K.ai[j] * hre[j]; \
;         hre[j] = MFMA16K16(K.Bf[2 * j], xb_, cre_); him[j] = MFMA16K16(K.Bf[2 * j + 1], xb_, cim_); } } while (0)
; __device__ __forceinline__ void s5_prompt_task(const Args& a, const Ctx& C, int b, int g, v4u (&xv)[8]) {
;     ...
;     for (int t = 0; t < 16; ++t) { const v2u xq = *(const LAS v2u*)(xsl + t * 32); S5_UPDATE(K, hre, him, xq); }
	v_mfma_f32_16x16x16_bf16 v[140:143], v[114:115], v[164:165], v[168:171]
	s_nop 2
	v_fma_f32 v170, v118, v174, v108
	v_fma_f32 v171, v119, v175, v109
	v_fma_f32 v168, v88, v172, v138
	v_fma_f32 v169, v89, v173, v139
	v_mul_f32_e32 v108, v120, v148
	v_mul_f32_e32 v109, v121, v149
	v_mul_f32_e32 v138, v94, v146
	v_mul_f32_e32 v139, v95, v147
	v_fma_f32 v174, v86, v178, -v108
	v_fma_f32 v175, v87, v179, -v109
	v_fma_f32 v172, v82, v176, -v138
	v_fma_f32 v173, v83, v177, -v139
	v_mul_f32_e32 v108, v86, v148
	v_mul_f32_e32 v109, v87, v149
	v_mul_f32_e32 v138, v82, v146
	v_mul_f32_e32 v139, v83, v147
	v_mfma_f32_16x16x16_bf16 v[168:171], v[116:117], v[164:165], v[168:171]
	v_fma_f32 v148, v120, v178, v108
	v_fma_f32 v149, v121, v179, v109
	v_fma_f32 v146, v94, v176, v138
	v_fma_f32 v147, v95, v177, v139
	v_mul_f32_e32 v108, v122, v152
	v_mul_f32_e32 v109, v123, v153
	v_mul_f32_e32 v138, v98, v150
	v_mul_f32_e32 v139, v99, v151
	v_fma_f32 v178, v92, v182, -v108
	v_fma_f32 v179, v93, v183, -v109
	v_fma_f32 v176, v84, v180, -v138
	v_fma_f32 v177, v85, v181, -v139
	v_mul_f32_e32 v138, v84, v150
	v_mul_f32_e32 v139, v85, v151
	v_mul_f32_e32 v108, v92, v152
	v_mul_f32_e32 v109, v93, v153
	v_mfma_f32_16x16x16_bf16 v[152:155], v[130:131], v[164:165], v[176:179]
	s_nop 2
	v_fma_f32 v176, v98, v180, v138
	v_fma_f32 v177, v99, v181, v139
	v_mul_f32_e32 v138, v100, v104
	v_mul_f32_e32 v139, v101, v105
	v_mfma_f32_16x16x16_bf16 v[146:149], v[128:129], v[164:165], v[146:149]
	v_fma_f32 v178, v122, v182, v108
	v_fma_f32 v179, v123, v183, v109
	v_mul_f32_e32 v108, v124, v106
	v_mul_f32_e32 v109, v125, v107
	v_fma_f32 v180, v90, v156, -v138
	v_fma_f32 v181, v91, v157, -v139
	v_mul_f32_e32 v138, v96, v106
	v_mul_f32_e32 v139, v97, v107
	v_mul_f32_e32 v104, v90, v104
	v_mul_f32_e32 v105, v91, v105
	v_mfma_f32_16x16x16_bf16 v[172:175], v[126:127], v[164:165], v[172:175]
	v_fma_f32 v182, v96, v158, -v108
	v_fma_f32 v183, v97, v159, -v109
	v_fma_f32 v158, v124, v158, v138
	v_fma_f32 v159, v125, v159, v139
	v_fma_f32 v156, v100, v156, v104
	v_fma_f32 v157, v101, v157, v105
	v_mul_f32_e32 v104, v118, v170
	v_mul_f32_e32 v105, v119, v171
	v_mul_f32_e32 v138, v88, v168
	v_mul_f32_e32 v139, v89, v169
	v_mfma_f32_16x16x16_bf16 v[176:179], v[132:133], v[164:165], v[176:179]
	v_mfma_f32_16x16x16_bf16 v[106:109], v[134:135], v[164:165], v[180:183]
	s_nop 2
	v_fma_f32 v182, v80, v142, -v104
	v_fma_f32 v183, v81, v143, -v105
	v_fma_f32 v180, v78, v140, -v138
	v_fma_f32 v181, v79, v141, -v139
	v_mul_f32_e32 v104, v80, v170
	v_mul_f32_e32 v105, v81, v171
	v_mul_f32_e32 v138, v78, v168
	v_mul_f32_e32 v139, v79, v169
	v_fma_f32 v142, v118, v142, v104
	v_fma_f32 v143, v119, v143, v105
	v_fma_f32 v140, v88, v140, v138
	v_fma_f32 v141, v89, v141, v139
	v_mfma_f32_16x16x16_bf16 v[156:159], v[136:137], v[164:165], v[156:159]
	v_mul_f32_e64 v104, v120, v148
	v_mul_f32_e64 v105, v121, v149
	v_fma_f32 v170, v86, v174, -v104
	v_fma_f32 v171, v87, v175, -v105
	v_mfma_f32_16x16x16_bf16 v[138:141], v[116:117], v[166:167], v[140:143]
	v_mul_f32_e64 v104, v86, v148
	v_mul_f32_e64 v105, v87, v149
	s_nop 0
	v_mul_f32_e32 v142, v94, v146
	v_mul_f32_e32 v143, v95, v147
	v_mfma_f32_16x16x16_bf16 v[180:183], v[114:115], v[166:167], v[180:183]
	v_fma_f32 v168, v82, v172, -v142
	v_fma_f32 v169, v83, v173, -v143
	v_mul_f32_e32 v142, v82, v146
	v_mul_f32_e32 v143, v83, v147
	s_nop 0
	v_mfma_f32_16x16x16_bf16 v[148:151], v[126:127], v[166:167], v[168:171]
	s_nop 2
	v_fma_f32 v170, v120, v174, v104
	v_fma_f32 v171, v121, v175, v105
	v_fma_f32 v168, v94, v172, v142
	v_fma_f32 v169, v95, v173, v143
	v_mul_f32_e32 v104, v122, v178
	v_mul_f32_e32 v105, v123, v179
	v_mul_f32_e32 v142, v98, v176
	v_mul_f32_e32 v143, v99, v177
	v_fma_f32 v174, v92, v154, -v104
	v_fma_f32 v175, v93, v155, -v105
	v_fma_f32 v172, v84, v152, -v142
	v_fma_f32 v173, v85, v153, -v143
	v_mul_f32_e32 v104, v92, v178
	v_mul_f32_e32 v105, v93, v179
	v_mul_f32_e32 v142, v84, v176
	v_mul_f32_e32 v143, v85, v177
	v_fma_f32 v154, v122, v154, v104
	v_fma_f32 v155, v123, v155, v105
	v_fma_f32 v152, v98, v152, v142
	v_fma_f32 v153, v99, v153, v143
	v_mul_f32_e32 v104, v124, v158
	v_mul_f32_e32 v105, v125, v159
	v_mul_f32_e32 v142, v100, v156
	v_mul_f32_e32 v143, v101, v157
	v_fma_f32 v178, v96, v108, -v104
	v_fma_f32 v179, v97, v109, -v105
	v_fma_f32 v176, v90, v106, -v142
	v_fma_f32 v177, v91, v107, -v143
	v_mul_f32_e32 v104, v96, v158
	v_mul_f32_e32 v105, v97, v159
	v_mul_f32_e32 v142, v90, v156
	v_mul_f32_e32 v143, v91, v157
	ds_read2_b64 v[156:159], v163 offset0:40 offset1:44
	v_mfma_f32_16x16x16_bf16 v[168:171], v[128:129], v[166:167], v[168:171]
	v_fma_f32 v108, v124, v108, v104
	v_fma_f32 v109, v125, v109, v105
	v_fma_f32 v106, v100, v106, v142
	v_fma_f32 v107, v101, v107, v143
	v_mul_f32_e32 v142, v88, v138
	v_mul_f32_e32 v143, v89, v139
	v_mfma_f32_16x16x16_bf16 v[152:155], v[132:133], v[166:167], v[152:155]
	v_fma_f32 v164, v78, v180, -v142
	v_fma_f32 v165, v79, v181, -v143
	v_mul_f32_e32 v138, v78, v138
	v_mul_f32_e32 v139, v79, v139
	v_mfma_f32_16x16x16_bf16 v[104:107], v[136:137], v[166:167], v[106:109]
	s_nop 2
	v_mul_f32_e64 v108, v118, v140
	v_mul_f32_e64 v109, v119, v141
	v_mfma_f32_16x16x16_bf16 v[172:175], v[130:131], v[166:167], v[172:175]
	v_mfma_f32_16x16x16_bf16 v[176:179], v[134:135], v[166:167], v[176:179]
	v_fma_f32 v166, v80, v182, -v108
	v_fma_f32 v167, v81, v183, -v109
	v_mul_f32_e32 v108, v80, v140
	v_mul_f32_e32 v109, v81, v141
	s_waitcnt lgkmcnt(0)
; #define LAS __attribute__((address_space(3)))
; #define S5_UPDATE(K, hre, him, xq) do { const v2u xb_ = (xq); \
;     _Pragma("unroll") for (int j = 0; j < 4; ++j) { const f32x4 cre_ = K.ar[j] * hre[j] - K.ai[j] * him[j], cim_ = K.ar[j] * him[j] + K.ai[j] * hre[j]; \
;         hre[j] = MFMA16K16(K.Bf[2 * j], xb_, cre_); him[j] = MFMA16K16(K.Bf[2 * j + 1], xb_, cim_); } } while (0)
; __device__ __forceinline__ void s5_prompt_task(const Args& a, const Ctx& C, int b, int g, v4u (&xv)[8]) {
;     ...
;     for (int t = 0; t < 16; ++t) { const v2u xq = *(const LAS v2u*)(xsl + t * 32); S5_UPDATE(K, hre, him, xq); }
	v_mfma_f32_16x16x16_bf16 v[140:143], v[114:115], v[156:157], v[164:167]
	s_nop 2
	v_fma_f32 v166, v118, v182, v108
	v_fma_f32 v167, v119, v183, v109
	v_fma_f32 v164, v88, v180, v138
	v_fma_f32 v165, v89, v181, v139
	v_mul_f32_e32 v108, v120, v170
	v_mul_f32_e32 v109, v121, v171
	v_mul_f32_e32 v138, v94, v168
	v_mul_f32_e32 v139, v95, v169
	v_fma_f32 v182, v86, v150, -v108
	v_fma_f32 v183, v87, v151, -v109
	v_fma_f32 v180, v82, v148, -v138
	v_fma_f32 v181, v83, v149, -v139
	v_mul_f32_e32 v108, v86, v170
	v_mul_f32_e32 v109, v87, v171
	v_mul_f32_e32 v138, v82, v168
	v_mul_f32_e32 v139, v83, v169
	v_mfma_f32_16x16x16_bf16 v[164:167], v[116:117], v[156:157], v[164:167]
	v_fma_f32 v150, v120, v150, v108
	v_fma_f32 v151, v121, v151, v109
	v_fma_f32 v148, v94, v148, v138
	v_fma_f32 v149, v95, v149, v139
	v_mul_f32_e32 v108, v122, v154
	v_mul_f32_e32 v109, v123, v155
	v_mul_f32_e32 v138, v98, v152
	v_mul_f32_e32 v139, v99, v153
	v_fma_f32 v170, v92, v174, -v108
	v_fma_f32 v171, v93, v175, -v109
	v_fma_f32 v168, v84, v172, -v138
	v_fma_f32 v169, v85, v173, -v139
	v_mul_f32_e32 v108, v92, v154
	v_mul_f32_e32 v109, v93, v155
	v_mul_f32_e32 v138, v84, v152
	v_mul_f32_e32 v139, v85, v153
	v_mfma_f32_16x16x16_bf16 v[146:149], v[128:129], v[156:157], v[148:151]
	v_fma_f32 v152, v122, v174, v108
	v_fma_f32 v153, v123, v175, v109
	v_mul_f32_e32 v108, v124, v106
	v_mul_f32_e32 v109, v125, v107
	v_fma_f32 v150, v98, v172, v138
	v_fma_f32 v151, v99, v173, v139
	v_mul_f32_e32 v138, v100, v104
	v_mul_f32_e32 v139, v101, v105
	v_fma_f32 v174, v96, v178, -v108
	v_fma_f32 v175, v97, v179, -v109
	v_fma_f32 v172, v90, v176, -v138
	v_fma_f32 v173, v91, v177, -v139
	v_mul_f32_e32 v138, v96, v106
	v_mul_f32_e32 v139, v97, v107
	v_mul_f32_e32 v104, v90, v104
	v_mul_f32_e32 v105, v91, v105
	v_mfma_f32_16x16x16_bf16 v[180:183], v[126:127], v[156:157], v[180:183]
	v_mfma_f32_16x16x16_bf16 v[106:109], v[134:135], v[156:157], v[172:175]
	s_nop 2
	v_fma_f32 v174, v124, v178, v138
	v_fma_f32 v175, v125, v179, v139
	v_fma_f32 v172, v100, v176, v104
	v_fma_f32 v173, v101, v177, v105
	v_mul_f32_e32 v104, v118, v166
	v_mul_f32_e32 v105, v119, v167
	v_mul_f32_e32 v138, v88, v164
	v_mul_f32_e32 v139, v89, v165
	v_mfma_f32_16x16x16_bf16 v[168:171], v[130:131], v[156:157], v[168:171]
	v_mfma_f32_16x16x16_bf16 v[150:153], v[132:133], v[156:157], v[150:153]
	v_mfma_f32_16x16x16_bf16 v[154:157], v[136:137], v[156:157], v[172:175]
	s_nop 2
	v_fma_f32 v174, v80, v142, -v104
	v_fma_f32 v175, v81, v143, -v105
	v_fma_f32 v172, v78, v140, -v138
	v_fma_f32 v173, v79, v141, -v139
	v_mul_f32_e32 v104, v80, v166
	v_mul_f32_e32 v105, v81, v167
	v_mul_f32_e32 v138, v78, v164
	v_mul_f32_e32 v139, v79, v165
	v_fma_f32 v142, v118, v142, v104
	v_fma_f32 v143, v119, v143, v105
	v_fma_f32 v140, v88, v140, v138
	v_fma_f32 v141, v89, v141, v139
	v_mul_f32_e32 v104, v120, v148
	v_mul_f32_e32 v105, v121, v149
	v_mfma_f32_16x16x16_bf16 v[172:175], v[114:115], v[158:159], v[172:175]
	v_fma_f32 v166, v86, v182, -v104
	v_fma_f32 v167, v87, v183, -v105
	v_mul_f32_e32 v104, v86, v148
	v_mul_f32_e32 v105, v87, v149
	v_mfma_f32_16x16x16_bf16 v[138:141], v[116:117], v[158:159], v[140:143]
	v_fma_f32 v148, v120, v182, v104
	v_fma_f32 v149, v121, v183, v105
	v_mul_f32_e32 v104, v122, v152
	v_mul_f32_e32 v105, v123, v153
	v_mul_f32_e32 v142, v94, v146
	v_mul_f32_e32 v143, v95, v147
	v_fma_f32 v178, v92, v170, -v104
	v_fma_f32 v179, v93, v171, -v105
	v_fma_f32 v164, v82, v180, -v142
	v_fma_f32 v165, v83, v181, -v143
	v_mul_f32_e32 v142, v82, v146
	v_mul_f32_e32 v143, v83, v147
	v_mul_f32_e32 v104, v92, v152
	v_mul_f32_e32 v105, v93, v153
	v_fma_f32 v146, v94, v180, v142
	v_fma_f32 v147, v95, v181, v143
	v_mul_f32_e32 v142, v98, v150
	v_mul_f32_e32 v143, v99, v151
	v_fma_f32 v152, v122, v170, v104
	v_fma_f32 v153, v123, v171, v105
	v_fma_f32 v176, v84, v168, -v142
	v_fma_f32 v177, v85, v169, -v143
	v_mul_f32_e32 v142, v84, v150
	v_mul_f32_e32 v143, v85, v151
	v_mul_f32_e32 v104, v124, v156
	v_mul_f32_e32 v105, v125, v157
	v_fma_f32 v150, v98, v168, v142
	v_fma_f32 v151, v99, v169, v143
	v_mul_f32_e32 v142, v100, v154
	v_mul_f32_e32 v143, v101, v155
	v_mfma_f32_16x16x16_bf16 v[146:149], v[128:129], v[158:159], v[146:149]
	v_fma_f32 v170, v96, v108, -v104
	v_fma_f32 v171, v97, v109, -v105
	v_fma_f32 v168, v90, v106, -v142
	v_fma_f32 v169, v91, v107, -v143
	v_mul_f32_e32 v104, v96, v156
	v_mul_f32_e32 v105, v97, v157
	v_mul_f32_e32 v142, v90, v154
	v_mul_f32_e32 v143, v91, v155
	ds_read2_b64 v[154:157], v163 offset0:48 offset1:52
	v_mfma_f32_16x16x16_bf16 v[164:167], v[126:127], v[158:159], v[164:167]
	v_fma_f32 v108, v124, v108, v104
	v_fma_f32 v109, v125, v109, v105
	v_fma_f32 v106, v100, v106, v142
	v_fma_f32 v107, v101, v107, v143
	v_mul_f32_e32 v142, v88, v138
	v_mul_f32_e32 v143, v89, v139
	v_mfma_f32_16x16x16_bf16 v[150:153], v[132:133], v[158:159], v[150:153]
	v_mul_f32_e64 v138, v78, v138
	v_mul_f32_e64 v139, v79, v139
	v_fma_f32 v180, v78, v172, -v142
	v_fma_f32 v181, v79, v173, -v143
	v_fma_f32 v172, v88, v172, v138
	v_fma_f32 v173, v89, v173, v139
	v_mfma_f32_16x16x16_bf16 v[176:179], v[130:131], v[158:159], v[176:179]
	v_mul_f32_e64 v138, v94, v146
	v_mul_f32_e64 v139, v95, v147
	v_mfma_f32_16x16x16_bf16 v[104:107], v[136:137], v[158:159], v[106:109]
	s_nop 2
	v_mul_f32_e64 v108, v118, v140
	v_mul_f32_e64 v109, v119, v141
	v_mfma_f32_16x16x16_bf16 v[168:171], v[134:135], v[158:159], v[168:171]
	v_fma_f32 v182, v80, v174, -v108
	v_fma_f32 v183, v81, v175, -v109
	v_mul_f32_e32 v108, v80, v140
	v_mul_f32_e32 v109, v81, v141
	s_waitcnt lgkmcnt(0)
; #define LAS __attribute__((address_space(3)))
; #define S5_UPDATE(K, hre, him, xq) do { const v2u xb_ = (xq); \
;     _Pragma("unroll") for (int j = 0; j < 4; ++j) { const f32x4 cre_ = K.ar[j] * hre[j] - K.ai[j] * him[j], cim_ = K.ar[j] * him[j] + K.ai[j] * hre[j]; \
;         hre[j] = MFMA16K16(K.Bf[2 * j], xb_, cre_); him[j] = MFMA16K16(K.Bf[2 * j + 1], xb_, cim_); } } while (0)
; __device__ __forceinline__ void s5_prompt_task(const Args& a, const Ctx& C, int b, int g, v4u (&xv)[8]) {
;     ...
;     for (int t = 0; t < 16; ++t) { const v2u xq = *(const LAS v2u*)(xsl + t * 32); S5_UPDATE(K, hre, him, xq); }
	v_mfma_f32_16x16x16_bf16 v[140:143], v[114:115], v[154:155], v[180:183]
	v_fma_f32 v174, v118, v174, v108
	v_fma_f32 v175, v119, v175, v109
	v_mul_f32_e32 v108, v120, v148
	v_mul_f32_e32 v109, v121, v149
	v_fma_f32 v180, v82, v164, -v138
	v_fma_f32 v181, v83, v165, -v139
	v_mul_f32_e32 v138, v82, v146
	v_mul_f32_e32 v139, v83, v147
	v_mfma_f32_16x16x16_bf16 v[172:175], v[116:117], v[154:155], v[172:175]
	v_fma_f32 v182, v86, v166, -v108
	v_fma_f32 v183, v87, v167, -v109
	v_mul_f32_e32 v108, v86, v148
	v_mul_f32_e32 v109, v87, v149
	v_fma_f32 v146, v94, v164, v138
	v_fma_f32 v147, v95, v165, v139
	v_mul_f32_e32 v138, v98, v150
	v_mul_f32_e32 v139, v99, v151
	v_fma_f32 v148, v120, v166, v108
	v_fma_f32 v149, v121, v167, v109
	v_mul_f32_e32 v108, v122, v152
	v_mul_f32_e32 v109, v123, v153
	v_fma_f32 v164, v84, v176, -v138
	v_fma_f32 v165, v85, v177, -v139
	v_mul_f32_e32 v138, v84, v150
	v_mul_f32_e32 v139, v85, v151
	v_fma_f32 v166, v92, v178, -v108
	v_fma_f32 v167, v93, v179, -v109
	v_mul_f32_e32 v108, v92, v152
	v_mul_f32_e32 v109, v93, v153
	v_fma_f32 v150, v98, v176, v138
	v_fma_f32 v151, v99, v177, v139
	v_mul_f32_e32 v138, v100, v104
	v_mul_f32_e32 v139, v101, v105
	v_mfma_f32_16x16x16_bf16 v[146:149], v[128:129], v[154:155], v[146:149]
	v_fma_f32 v152, v122, v178, v108
	v_fma_f32 v153, v123, v179, v109
	v_mul_f32_e32 v108, v124, v106
	v_mul_f32_e32 v109, v125, v107
	v_fma_f32 v176, v90, v168, -v138
	v_fma_f32 v177, v91, v169, -v139
	v_mul_f32_e32 v138, v96, v106
	v_mul_f32_e32 v139, v97, v107
	v_mul_f32_e32 v104, v90, v104
	v_mul_f32_e32 v105, v91, v105
	v_mfma_f32_16x16x16_bf16 v[180:183], v[126:127], v[154:155], v[180:183]
	v_fma_f32 v178, v96, v170, -v108
	v_fma_f32 v179, v97, v171, -v109
	v_fma_f32 v170, v124, v170, v138
	v_fma_f32 v171, v125, v171, v139
	v_fma_f32 v168, v100, v168, v104
	v_fma_f32 v169, v101, v169, v105
	v_mul_f32_e32 v104, v118, v174
	v_mul_f32_e32 v105, v119, v175
	v_mul_f32_e32 v138, v88, v172
	v_mul_f32_e32 v139, v89, v173
	v_mfma_f32_16x16x16_bf16 v[150:153], v[132:133], v[154:155], v[150:153]
	v_mfma_f32_16x16x16_bf16 v[106:109], v[134:135], v[154:155], v[176:179]
	s_nop 2
	v_fma_f32 v178, v80, v142, -v104
	v_fma_f32 v179, v81, v143, -v105
	v_fma_f32 v176, v78, v140, -v138
	v_fma_f32 v177, v79, v141, -v139
	v_mul_f32_e32 v104, v80, v174
	v_mul_f32_e32 v105, v81, v175
	v_mul_f32_e32 v138, v78, v172
	v_mul_f32_e32 v139, v79, v173
	v_mfma_f32_16x16x16_bf16 v[164:167], v[130:131], v[154:155], v[164:167]
	v_fma_f32 v142, v118, v142, v104
	v_fma_f32 v143, v119, v143, v105
	v_fma_f32 v140, v88, v140, v138
	v_fma_f32 v141, v89, v141, v139
	v_mul_f32_e32 v104, v120, v148
	v_mul_f32_e32 v105, v121, v149
	v_mfma_f32_16x16x16_bf16 v[168:171], v[136:137], v[154:155], v[168:171]
	v_fma_f32 v186, v86, v182, -v104
	v_fma_f32 v187, v87, v183, -v105
	v_mul_f32_e32 v104, v86, v148
	v_mul_f32_e32 v105, v87, v149
	v_mfma_f32_16x16x16_bf16 v[138:141], v[116:117], v[156:157], v[140:143]
	v_fma_f32 v148, v120, v182, v104
	v_fma_f32 v149, v121, v183, v105
	v_mul_f32_e32 v104, v122, v152
	v_mul_f32_e32 v105, v123, v153
	v_mul_f32_e32 v142, v94, v146
	v_mul_f32_e32 v143, v95, v147
	v_mfma_f32_16x16x16_bf16 v[174:177], v[114:115], v[156:157], v[176:179]
	v_fma_f32 v184, v82, v180, -v142
	v_fma_f32 v185, v83, v181, -v143
	v_mul_f32_e32 v142, v82, v146
	v_mul_f32_e32 v143, v83, v147
	s_nop 0
	v_fma_f32 v146, v94, v180, v142
	v_fma_f32 v147, v95, v181, v143
	v_mul_f32_e32 v142, v98, v150
	v_mul_f32_e32 v143, v99, v151
	v_fma_f32 v180, v92, v166, -v104
	v_fma_f32 v181, v93, v167, -v105
	v_fma_f32 v178, v84, v164, -v142
	v_fma_f32 v179, v85, v165, -v143
	v_mul_f32_e32 v104, v92, v152
	v_mul_f32_e32 v105, v93, v153
	v_mul_f32_e32 v142, v84, v150
	v_mul_f32_e32 v143, v85, v151
	v_fma_f32 v166, v122, v166, v104
	v_fma_f32 v167, v123, v167, v105
	v_fma_f32 v164, v98, v164, v142
	v_fma_f32 v165, v99, v165, v143
	v_mul_f32_e32 v104, v124, v170
	v_mul_f32_e32 v105, v125, v171
	v_mul_f32_e32 v142, v100, v168
	v_mul_f32_e32 v143, v101, v169
	v_mfma_f32_16x16x16_bf16 v[152:155], v[130:131], v[156:157], v[178:181]
	s_nop 2
	v_fma_f32 v180, v96, v108, -v104
	v_fma_f32 v181, v97, v109, -v105
	v_fma_f32 v178, v90, v106, -v142
	v_fma_f32 v179, v91, v107, -v143
	v_mul_f32_e32 v104, v96, v170
	v_mul_f32_e32 v105, v97, v171
	v_mul_f32_e32 v142, v90, v168
	v_mul_f32_e32 v143, v91, v169
	v_fma_f32 v108, v124, v108, v104
	v_fma_f32 v109, v125, v109, v105
	v_fma_f32 v106, v100, v106, v142
	v_fma_f32 v107, v101, v107, v143
	v_mfma_f32_16x16x16_bf16 v[184:187], v[126:127], v[156:157], v[184:187]
	v_mul_f32_e64 v142, v88, v138
	v_mul_f32_e64 v143, v89, v139
	v_mul_f32_e32 v138, v78, v138
	v_mul_f32_e32 v139, v79, v139
	v_mfma_f32_16x16x16_bf16 v[146:149], v[128:129], v[156:157], v[146:149]
	v_mfma_f32_16x16x16_bf16 v[164:167], v[132:133], v[156:157], v[164:167]
	v_mfma_f32_16x16x16_bf16 v[170:173], v[134:135], v[156:157], v[178:181]
	v_mfma_f32_16x16x16_bf16 v[104:107], v[136:137], v[156:157], v[106:109]
	ds_read2_b64 v[156:159], v163 offset0:56 offset1:60
	s_nop 0
	v_fma_f32 v178, v78, v174, -v142
	v_fma_f32 v179, v79, v175, -v143
	v_fma_f32 v174, v88, v174, v138
	v_fma_f32 v175, v89, v175, v139
	v_mul_f32_e32 v108, v118, v140
	v_mul_f32_e32 v109, v119, v141
	v_mul_f32_e32 v138, v94, v146
	v_mul_f32_e32 v139, v95, v147
	v_fma_f32 v180, v80, v176, -v108
	v_fma_f32 v181, v81, v177, -v109
	v_mul_f32_e32 v108, v80, v140
	v_mul_f32_e32 v109, v81, v141
	s_nop 0
	v_fma_f32 v176, v118, v176, v108
	v_fma_f32 v177, v119, v177, v109
	v_mul_f32_e32 v108, v120, v148
	v_mul_f32_e32 v109, v121, v149
	s_waitcnt lgkmcnt(0)
; #define LAS __attribute__((address_space(3)))
; #define S5_UPDATE(K, hre, him, xq) do { const v2u xb_ = (xq); \
;     _Pragma("unroll") for (int j = 0; j < 4; ++j) { const f32x4 cre_ = K.ar[j] * hre[j] - K.ai[j] * him[j], cim_ = K.ar[j] * him[j] + K.ai[j] * hre[j]; \
;         hre[j] = MFMA16K16(K.Bf[2 * j], xb_, cre_); him[j] = MFMA16K16(K.Bf[2 * j + 1], xb_, cim_); } } while (0)
; __device__ __forceinline__ void s5_prompt_task(const Args& a, const Ctx& C, int b, int g, v4u (&xv)[8]) {
;     ...
;     for (int t = 0; t < 16; ++t) { const v2u xq = *(const LAS v2u*)(xsl + t * 32); S5_UPDATE(K, hre, him, xq); }
; #pragma unroll
;     for (int j = 0; j < 4; ++j) { LAS float* d = SH + chunk * 132 + 2 * (16 * j + 4 * q);
;         *(LAS f32x4*)d = (f32x4){hre[j][0], him[j][0], hre[j][1], him[j][1]}; *(LAS f32x4*)(d + 4) = (f32x4){hre[j][2], him[j][2], hre[j][3], him[j][3]}; }
;     v2u zq[4];
; #pragma unroll
;     for (int t = 0; t < 4; ++t) zq[t] = __builtin_nontemporal_load((const v2u*)(ZBg + (size_t)(16 * chunk + t) * 16 + 4 * q));
	v_mfma_f32_16x16x16_bf16 v[140:143], v[114:115], v[156:157], v[178:181]
	s_nop 2
	v_fma_f32 v180, v86, v186, -v108
	v_fma_f32 v181, v87, v187, -v109
	v_fma_f32 v178, v82, v184, -v138
	v_fma_f32 v179, v83, v185, -v139
	v_mul_f32_e32 v138, v82, v146
	v_mul_f32_e32 v139, v83, v147
	v_mfma_f32_16x16x16_bf16 v[174:177], v[116:117], v[156:157], v[174:177]
	v_mul_f32_e64 v108, v86, v148
	v_mul_f32_e64 v109, v87, v149
	v_mfma_f32_16x16x16_bf16 v[148:151], v[126:127], v[156:157], v[178:181]
	s_nop 2
	v_fma_f32 v178, v94, v184, v138
	v_fma_f32 v179, v95, v185, v139
	v_mul_f32_e32 v138, v98, v164
	v_mul_f32_e32 v139, v99, v165
	v_fma_f32 v180, v120, v186, v108
	v_fma_f32 v181, v121, v187, v109
	v_mul_f32_e32 v108, v122, v166
	v_mul_f32_e32 v109, v123, v167
	v_fma_f32 v182, v84, v152, -v138
	v_fma_f32 v183, v85, v153, -v139
	v_mul_f32_e32 v138, v84, v164
	v_mul_f32_e32 v139, v85, v165
	v_mfma_f32_16x16x16_bf16 v[178:181], v[128:129], v[156:157], v[178:181]
	v_fma_f32 v184, v92, v154, -v108
	v_fma_f32 v185, v93, v155, -v109
	v_mul_f32_e32 v108, v92, v166
	v_mul_f32_e32 v109, v93, v167
	v_fma_f32 v152, v98, v152, v138
	v_fma_f32 v153, v99, v153, v139
	v_mul_f32_e32 v138, v100, v104
	v_mul_f32_e32 v139, v101, v105
	v_mfma_f32_16x16x16_bf16 v[166:169], v[130:131], v[156:157], v[182:185]
	v_fma_f32 v154, v122, v154, v108
	v_fma_f32 v155, v123, v155, v109
	v_mul_f32_e32 v108, v124, v106
	v_mul_f32_e32 v109, v125, v107
	v_mul_f32_e32 v104, v90, v104
	v_mul_f32_e32 v105, v91, v105
	v_fma_f32 v182, v90, v170, -v138
	v_fma_f32 v183, v91, v171, -v139
	v_mul_f32_e32 v138, v96, v106
	v_mul_f32_e32 v139, v97, v107
	v_mfma_f32_16x16x16_bf16 v[152:155], v[132:133], v[156:157], v[152:155]
	v_fma_f32 v184, v96, v172, -v108
	v_fma_f32 v185, v97, v173, -v109
	v_fma_f32 v172, v124, v172, v138
	v_fma_f32 v173, v125, v173, v139
	v_mul_f32_e32 v138, v88, v174
	v_mul_f32_e32 v139, v89, v175
	v_mfma_f32_16x16x16_bf16 v[106:109], v[134:135], v[156:157], v[182:185]
	v_fma_f32 v170, v100, v170, v104
	v_fma_f32 v171, v101, v171, v105
	v_mul_f32_e32 v104, v118, v176
	v_mul_f32_e32 v105, v119, v177
	v_fma_f32 v182, v78, v140, -v138
	v_fma_f32 v183, v79, v141, -v139
	v_mul_f32_e32 v78, v78, v174
	v_mul_f32_e32 v79, v79, v175
	v_mfma_f32_16x16x16_bf16 v[170:173], v[136:137], v[156:157], v[170:173]
	v_fma_f32 v184, v80, v142, -v104
	v_fma_f32 v185, v81, v143, -v105
	v_fma_f32 v78, v88, v140, v78
	v_fma_f32 v79, v89, v141, v79
	v_mul_f32_e32 v88, v120, v180
	v_mul_f32_e32 v89, v121, v181
	v_mul_f32_e32 v104, v94, v178
	v_mul_f32_e32 v105, v95, v179
	v_fma_f32 v140, v86, v150, -v88
	v_fma_f32 v141, v87, v151, -v89
	v_fma_f32 v138, v82, v148, -v104
	v_fma_f32 v139, v83, v149, -v105
	v_mul_f32_e32 v82, v82, v178
	v_mul_f32_e32 v83, v83, v179
	v_mul_f32_e32 v80, v80, v176
	v_mul_f32_e32 v81, v81, v177
	v_mul_f32_e32 v104, v86, v180
	v_mul_f32_e32 v105, v87, v181
	v_mfma_f32_16x16x16_bf16 v[86:89], v[126:127], v[158:159], v[138:141]
	v_fma_f32 v80, v118, v142, v80
	v_fma_f32 v81, v119, v143, v81
	s_nop 0
	v_fma_f32 v138, v94, v148, v82
	v_fma_f32 v139, v95, v149, v83
	v_mul_f32_e32 v82, v122, v154
	v_mul_f32_e32 v83, v123, v155
	v_fma_f32 v140, v120, v150, v104
	v_fma_f32 v141, v121, v151, v105
	v_mul_f32_e32 v94, v98, v152
	v_mul_f32_e32 v95, v99, v153
	v_fma_f32 v148, v92, v168, -v82
	v_fma_f32 v149, v93, v169, -v83
	v_mul_f32_e32 v82, v92, v154
	v_mul_f32_e32 v83, v93, v155
	v_mul_f32_e32 v104, v84, v152
	v_mul_f32_e32 v105, v85, v153
	v_mfma_f32_16x16x16_bf16 v[182:185], v[114:115], v[158:159], v[182:185]
	v_fma_f32 v146, v84, v166, -v94
	v_fma_f32 v147, v85, v167, -v95
	v_fma_f32 v84, v122, v168, v82
	v_fma_f32 v85, v123, v169, v83
	v_fma_f32 v82, v98, v166, v104
	v_fma_f32 v83, v99, v167, v105
	v_mfma_f32_16x16x16_bf16 v[78:81], v[116:117], v[158:159], v[78:81]
	v_mul_f32_e64 v104, v100, v170
	v_mul_f32_e64 v105, v101, v171
	v_mul_f32_e32 v98, v124, v172
	v_mul_f32_e32 v99, v125, v173
	v_mov_b32_e32 v102, v183
	v_mfma_f32_16x16x16_bf16 v[138:141], v[128:129], v[158:159], v[138:141]
	v_lshlrev_b32_e32 v152, 3, v162
	s_nop 1
	v_mov_b32_e32 v103, v79
	v_mov_b32_e32 v79, v80
	v_mfma_f32_16x16x16_bf16 v[92:95], v[130:131], v[158:159], v[146:149]
	v_mov_b32_e32 v80, v185
	v_mov_b32_e32 v153, v111
	s_nop 0
	v_fma_f32 v146, v90, v106, -v104
	v_fma_f32 v147, v91, v107, -v105
	v_mul_f32_e32 v104, v96, v172
	v_mul_f32_e32 v105, v97, v173
	v_mul_f32_e32 v90, v90, v170
	v_mul_f32_e32 v91, v91, v171
	v_mfma_f32_16x16x16_bf16 v[82:85], v[132:133], v[158:159], v[82:85]
	v_fma_f32 v148, v96, v108, -v98
	v_fma_f32 v149, v97, v109, -v99
	v_fma_f32 v108, v124, v108, v104
	v_fma_f32 v109, v125, v109, v105
	v_fma_f32 v106, v100, v106, v90
	v_fma_f32 v107, v101, v107, v91
	v_mfma_f32_16x16x16_bf16 v[96:99], v[134:135], v[158:159], v[146:149]
	v_mov_b32_e32 v101, v78
	v_mov_b32_e32 v78, v184
	ds_write_b128 v3, v[78:81] offset:16
	v_mfma_f32_16x16x16_bf16 v[104:107], v[136:137], v[158:159], v[106:109]
	v_mov_b32_e32 v78, v86
	v_mov_b32_e32 v79, v138
	v_mov_b32_e32 v80, v87
	v_mov_b32_e32 v81, v139
	ds_write_b128 v3, v[78:81] offset:128
	v_mov_b32_e32 v78, v92
	v_mov_b32_e32 v79, v82
	v_mov_b32_e32 v80, v93
	v_mov_b32_e32 v81, v83
	ds_write_b128 v3, v[78:81] offset:256
	v_mov_b32_e32 v78, v96
	v_mov_b32_e32 v79, v104
	v_mov_b32_e32 v80, v97
	v_mov_b32_e32 v81, v105
	v_mov_b32_e32 v138, v88
	v_mov_b32_e32 v139, v140
	v_mov_b32_e32 v140, v89
	v_mov_b32_e32 v82, v94
	v_mov_b32_e32 v83, v84
	v_mov_b32_e32 v84, v95
	ds_write_b128 v3, v[78:81] offset:384
	v_lshl_add_u64 v[78:79], s[4:5], 0, v[110:111]
	s_mov_b64 s[4:5], 0xd400000
	v_mov_b32_e32 v110, v7
	v_mov_b32_e32 v100, v182
	ds_write_b128 v3, v[138:141] offset:144
	ds_write_b128 v3, v[82:85] offset:272
	v_mov_b32_e32 v104, v98
	v_mov_b32_e32 v105, v106
	v_mov_b32_e32 v106, v99
	v_lshl_add_u64 v[138:139], v[78:79], 0, s[4:5]
	v_lshlrev_b64 v[78:79], 5, v[110:111]
	v_or_b32_e32 v80, 1, v7
	v_mov_b32_e32 v81, v111
	v_or_b32_e32 v82, 2, v7
	v_mov_b32_e32 v83, v111
	v_or_b32_e32 v84, 3, v7
	v_mov_b32_e32 v85, v111
	ds_write_b128 v3, v[100:103]
	ds_write_b128 v3, v[104:107] offset:400
	v_lshl_add_u64 v[78:79], v[138:139], 0, v[78:79]
	v_lshlrev_b64 v[80:81], 5, v[80:81]
	v_lshlrev_b64 v[82:83], 5, v[82:83]
	v_lshlrev_b64 v[84:85], 5, v[84:85]
	v_lshl_add_u64 v[80:81], v[138:139], 0, v[80:81]
	v_lshl_add_u64 v[82:83], v[138:139], 0, v[82:83]
	v_lshl_add_u64 v[84:85], v[138:139], 0, v[84:85]
	global_load_dwordx2 v[226:227], v[78:79], off nt
	global_load_dwordx2 v[228:229], v[80:81], off nt
	global_load_dwordx2 v[230:231], v[82:83], off nt
	global_load_dwordx2 v[232:233], v[84:85], off nt
	v_lshl_add_u64 v[78:79], s[6:7], 0, v[152:153]
	v_add_co_u32_e32 v80, vcc, s2, v78
	s_waitcnt lgkmcnt(0)
; #define LAS __attribute__((address_space(3)))
; #define LDS_WAIT() asm volatile("s_waitcnt lgkmcnt(0)" ::: "memory")
; __device__ __forceinline__ void s5_prompt_task(const Args& a, const Ctx& C, int b, int g, v4u (&xv)[8]) {
;     ...
;     LDS_WAIT();
;     { const float* A16 = (const float*)(a.ws + WS_S5C + S5C_A16) + (size_t)g * 128; const float* A256 = (const float*)(a.ws + WS_S5C + S5C_A256) + (size_t)g * 128;
;       const float a16r = A16[2 * lane], a16i = A16[2 * lane + 1], a256r = A256[2 * lane], a256i = A256[2 * lane + 1];
;       v2f sv[16];
; #pragma unroll
;       for (int i = 0; i < 16; ++i) sv[i] = *(const LAS v2f*)(SH + (16 * w + i) * 132 + 2 * lane);
;       float tr = 0.f, ti = 0.f;
; #pragma unroll
;       for (int i = 0; i < 16; ++i) { const float nr = a16r * tr - a16i * ti + sv[i][0], ni = a16r * ti + a16i * tr + sv[i][1]; tr = nr; ti = ni; }
;       TW[w * 128 + 2 * lane] = tr; TW[w * 128 + 2 * lane + 1] = ti;
;       __syncthreads();
	s_mov_b32 s2, 0x2310000
	s_nop 0
	v_addc_co_u32_e32 v81, vcc, 0, v79, vcc
	v_add_co_u32_e32 v78, vcc, s2, v78
	v_add_u32_e32 v7, s8, v152
	s_nop 0
	v_addc_co_u32_e32 v79, vcc, 0, v79, vcc
	s_mul_i32 s4, s82, 0x2100
	v_add_u32_e32 v7, s4, v7
	v_add_u32_e32 v11, 0x800, v7
	ds_read2_b64 v[106:109], v7 offset1:66
	ds_read2_b64 v[102:105], v7 offset0:132 offset1:198
	ds_read2_b64 v[98:101], v11 offset0:8 offset1:74
	ds_read2_b64 v[94:97], v11 offset0:140 offset1:206
	v_add_u32_e32 v11, 0x1000, v7
	ds_read2_b64 v[90:93], v11 offset0:16 offset1:82
	ds_read2_b64 v[86:89], v11 offset0:148 offset1:214
	v_add_u32_e32 v11, 0x1800, v7
	ds_read2_b64 v[82:85], v11 offset0:24 offset1:90
	ds_read2_b64 v[78:81], v11 offset0:156 offset1:222
	s_lshl_b32 s4, s82, 9
	s_add_i32 s4, s4, 0
	s_mov_b32 s2, 0
	s_cmp_lt_u32 s84, 64
	s_waitcnt vmcnt(4)
	v_mov_b32_e32 v148, v234
	v_mov_b32_e32 v149, v235
	v_mov_b32_e32 v150, v236
	v_mov_b32_e32 v151, v237
	v_mul_f32_e32 v11, 0, v148
	v_mul_f32_e32 v155, 0, v149
	v_sub_f32_e32 v154, v11, v155
	v_fmac_f32_e32 v155, 0, v148
	s_waitcnt lgkmcnt(7)
	v_pk_add_f32 v[154:155], v[154:155], v[106:107]
	v_add_u32_e32 v11, s4, v152
	v_pk_mul_f32 v[156:157], v[148:149], v[154:155] op_sel:[1,1] op_sel_hi:[0,1]
	v_pk_fma_f32 v[158:159], v[148:149], v[154:155], v[156:157] op_sel_hi:[1,0,1]
	v_pk_fma_f32 v[156:157], v[148:149], v[154:155], v[156:157] op_sel_hi:[1,0,1] neg_lo:[0,0,1] neg_hi:[0,0,1]
	v_add_u32_e32 v11, 0x21000, v11
	v_mov_b32_e32 v157, v159
	v_pk_add_f32 v[156:157], v[108:109], v[156:157]
	v_mov_b32_e32 v152, v111
	v_pk_mul_f32 v[158:159], v[148:149], v[156:157] op_sel:[1,1] op_sel_hi:[0,1]
	v_pk_fma_f32 v[164:165], v[148:149], v[156:157], v[158:159] op_sel_hi:[1,0,1]
	v_pk_fma_f32 v[158:159], v[148:149], v[156:157], v[158:159] op_sel_hi:[1,0,1] neg_lo:[0,0,1] neg_hi:[0,0,1]
	s_nop 0
	v_mov_b32_e32 v159, v165
	s_waitcnt lgkmcnt(6)
	v_pk_add_f32 v[158:159], v[102:103], v[158:159]
	s_nop 0
	v_pk_mul_f32 v[164:165], v[148:149], v[158:159] op_sel:[1,1] op_sel_hi:[0,1]
	v_pk_fma_f32 v[166:167], v[148:149], v[158:159], v[164:165] op_sel_hi:[1,0,1]
	v_pk_fma_f32 v[164:165], v[148:149], v[158:159], v[164:165] op_sel_hi:[1,0,1] neg_lo:[0,0,1] neg_hi:[0,0,1]
	s_nop 0
	v_mov_b32_e32 v165, v167
	v_pk_add_f32 v[164:165], v[104:105], v[164:165]
	s_nop 0
	v_pk_mul_f32 v[166:167], v[148:149], v[164:165] op_sel:[1,1] op_sel_hi:[0,1]
	v_pk_fma_f32 v[168:169], v[148:149], v[164:165], v[166:167] op_sel_hi:[1,0,1]
	v_pk_fma_f32 v[166:167], v[148:149], v[164:165], v[166:167] op_sel_hi:[1,0,1] neg_lo:[0,0,1] neg_hi:[0,0,1]
	s_nop 0
	v_mov_b32_e32 v167, v169
	s_waitcnt lgkmcnt(5)
	v_pk_add_f32 v[166:167], v[98:99], v[166:167]
	s_nop 0
	v_pk_mul_f32 v[168:169], v[148:149], v[166:167] op_sel:[1,1] op_sel_hi:[0,1]
	v_pk_fma_f32 v[170:171], v[148:149], v[166:167], v[168:169] op_sel_hi:[1,0,1]
	v_pk_fma_f32 v[168:169], v[148:149], v[166:167], v[168:169] op_sel_hi:[1,0,1] neg_lo:[0,0,1] neg_hi:[0,0,1]
	s_nop 0
	v_mov_b32_e32 v169, v171
	v_pk_add_f32 v[168:169], v[100:101], v[168:169]
	s_nop 0
	v_pk_mul_f32 v[170:171], v[148:149], v[168:169] op_sel:[1,1] op_sel_hi:[0,1]
	v_pk_fma_f32 v[172:173], v[148:149], v[168:169], v[170:171] op_sel_hi:[1,0,1]
	v_pk_fma_f32 v[170:171], v[148:149], v[168:169], v[170:171] op_sel_hi:[1,0,1] neg_lo:[0,0,1] neg_hi:[0,0,1]
	s_nop 0
	v_mov_b32_e32 v171, v173
	s_waitcnt lgkmcnt(4)
	v_pk_add_f32 v[170:171], v[94:95], v[170:171]
	s_nop 0
	v_pk_mul_f32 v[172:173], v[148:149], v[170:171] op_sel:[1,1] op_sel_hi:[0,1]
	v_pk_fma_f32 v[174:175], v[148:149], v[170:171], v[172:173] op_sel_hi:[1,0,1]
	v_pk_fma_f32 v[172:173], v[148:149], v[170:171], v[172:173] op_sel_hi:[1,0,1] neg_lo:[0,0,1] neg_hi:[0,0,1]
	s_nop 0
	v_mov_b32_e32 v173, v175
	v_pk_add_f32 v[172:173], v[96:97], v[172:173]
	s_nop 0
	v_pk_mul_f32 v[174:175], v[148:149], v[172:173] op_sel:[1,1] op_sel_hi:[0,1]
	v_pk_fma_f32 v[176:177], v[148:149], v[172:173], v[174:175] op_sel_hi:[1,0,1]
	v_pk_fma_f32 v[174:175], v[148:149], v[172:173], v[174:175] op_sel_hi:[1,0,1] neg_lo:[0,0,1] neg_hi:[0,0,1]
	s_nop 0
	v_mov_b32_e32 v175, v177
	s_waitcnt lgkmcnt(3)
	v_pk_add_f32 v[174:175], v[90:91], v[174:175]
	s_nop 0
	v_pk_mul_f32 v[176:177], v[148:149], v[174:175] op_sel:[1,1] op_sel_hi:[0,1]
	v_pk_fma_f32 v[178:179], v[148:149], v[174:175], v[176:177] op_sel_hi:[1,0,1]
	v_pk_fma_f32 v[176:177], v[148:149], v[174:175], v[176:177] op_sel_hi:[1,0,1] neg_lo:[0,0,1] neg_hi:[0,0,1]
	s_nop 0
	v_mov_b32_e32 v177, v179
	v_pk_add_f32 v[176:177], v[92:93], v[176:177]
	s_nop 0
	v_pk_mul_f32 v[178:179], v[148:149], v[176:177] op_sel:[1,1] op_sel_hi:[0,1]
	v_pk_fma_f32 v[180:181], v[148:149], v[176:177], v[178:179] op_sel_hi:[1,0,1]
	v_pk_fma_f32 v[178:179], v[148:149], v[176:177], v[178:179] op_sel_hi:[1,0,1] neg_lo:[0,0,1] neg_hi:[0,0,1]
	s_nop 0
	v_mov_b32_e32 v179, v181
	s_waitcnt lgkmcnt(2)
	v_pk_add_f32 v[178:179], v[86:87], v[178:179]
	s_nop 0
	v_pk_mul_f32 v[180:181], v[148:149], v[178:179] op_sel:[1,1] op_sel_hi:[0,1]
	v_pk_fma_f32 v[182:183], v[148:149], v[178:179], v[180:181] op_sel_hi:[1,0,1]
	v_pk_fma_f32 v[180:181], v[148:149], v[178:179], v[180:181] op_sel_hi:[1,0,1] neg_lo:[0,0,1] neg_hi:[0,0,1]
	s_nop 0
	v_mov_b32_e32 v181, v183
	v_pk_add_f32 v[182:183], v[88:89], v[180:181]
	s_nop 0
	v_pk_mul_f32 v[180:181], v[148:149], v[182:183] op_sel:[1,1] op_sel_hi:[0,1]
	v_pk_fma_f32 v[184:185], v[148:149], v[182:183], v[180:181] op_sel_hi:[1,0,1]
	v_pk_fma_f32 v[180:181], v[148:149], v[182:183], v[180:181] op_sel_hi:[1,0,1] neg_lo:[0,0,1] neg_hi:[0,0,1]
	s_nop 0
	v_mov_b32_e32 v181, v185
	s_waitcnt lgkmcnt(1)
	v_pk_add_f32 v[184:185], v[82:83], v[180:181]
	s_nop 0
	v_pk_mul_f32 v[180:181], v[148:149], v[184:185] op_sel:[1,1] op_sel_hi:[0,1]
	v_pk_fma_f32 v[186:187], v[148:149], v[184:185], v[180:181] op_sel_hi:[1,0,1]
	v_pk_fma_f32 v[180:181], v[148:149], v[184:185], v[180:181] op_sel_hi:[1,0,1] neg_lo:[0,0,1] neg_hi:[0,0,1]
	s_nop 0
	v_mov_b32_e32 v181, v187
	v_pk_add_f32 v[186:187], v[84:85], v[180:181]
	s_nop 0
	v_pk_mul_f32 v[180:181], v[148:149], v[186:187] op_sel:[1,1] op_sel_hi:[0,1]
	v_pk_fma_f32 v[188:189], v[148:149], v[186:187], v[180:181] op_sel_hi:[1,0,1]
	v_pk_fma_f32 v[180:181], v[148:149], v[186:187], v[180:181] op_sel_hi:[1,0,1] neg_lo:[0,0,1] neg_hi:[0,0,1]
	s_nop 0
	v_mov_b32_e32 v181, v189
	s_waitcnt lgkmcnt(0)
	v_pk_add_f32 v[188:189], v[78:79], v[180:181]
	s_nop 0
	v_pk_mul_f32 v[180:181], v[148:149], v[188:189] op_sel:[1,1] op_sel_hi:[0,1]
	v_pk_fma_f32 v[198:199], v[148:149], v[188:189], v[180:181] op_sel_hi:[1,0,1]
	v_pk_fma_f32 v[180:181], v[148:149], v[188:189], v[180:181] op_sel_hi:[1,0,1] neg_lo:[0,0,1] neg_hi:[0,0,1]
	s_nop 0
	v_mov_b32_e32 v181, v199
	v_pk_add_f32 v[180:181], v[80:81], v[180:181]
	ds_write_b64 v11, v[180:181]
	s_waitcnt lgkmcnt(0)
	s_barrier
; __device__ __forceinline__ void s5_prompt_task(const Args& a, const Ctx& C, int b, int g, v4u (&xv)[8]) {
;     ...
;       float hr = 0.f, hi = 0.f;
;       for (int v = 0; v < w; ++v) { const float sr = TW[v * 128 + 2 * lane], si = TW[v * 128 + 2 * lane + 1];
;           const float nr = a256r * hr - a256i * hi + sr, ni = a256r * hi + a256i * hr + si; hr = nr; hi = ni; }
	s_cbranch_scc1 .LBB0_985
	s_add_i32 s4, s82, -1
	s_cmp_lt_u32 s4, 7
	v_mov_b32_e32 v160, v111
	v_mov_b32_e32 v152, v111
	s_cbranch_scc1 .LBB0_977
	v_lshl_add_u32 v11, v162, 3, 0
	s_and_b32 s2, s82, 0x3fffff8
	s_waitcnt vmcnt(4)
	v_pk_mov_b32 v[154:155], v[150:151], v[150:151] op_sel:[1,0]
	s_mov_b32 s4, 0
	v_add_u32_e32 v11, 0x21000, v11
	v_mov_b32_e32 v152, 0
	v_mov_b32_e32 v160, 0

; #define LAS __attribute__((address_space(3)))
; #define MFMA16(A, B, Cc) __builtin_amdgcn_mfma_f32_16x16x32_bf16((A), (B), (Cc), 0, 0, 0)
; #define MFMA16K16(A, B, Cc) __builtin_amdgcn_mfma_f32_16x16x16bf16_1k(__builtin_bit_cast(bf16x4, (A)), __builtin_bit_cast(bf16x4, (B)), (Cc), 0, 0, 0)
; __device__ __forceinline__ unsigned pk2(float lo, float hi) { return pg8::cvt_pk_bf16(lo, hi); }
; __device__ __forceinline__ float bf_lo(unsigned w) { return __uint_as_float(w << 16); }
; __device__ __forceinline__ float bf_hi(unsigned w) { return __uint_as_float(w & 0xffff0000u); }
; __device__ __forceinline__ bf16x8 pack8(f32x4 lo, f32x4 hi) { v4u w; w.x = pk2(lo[0], lo[1]); w.y = pk2(lo[2], lo[3]); w.z = pk2(hi[0], hi[1]); w.w = pk2(hi[2], hi[3]); return __builtin_bit_cast(bf16x8, w); }
; #define S5_UPDATE(K, hre, him, xq) do { const v2u xb_ = (xq); \
;     _Pragma("unroll") for (int j = 0; j < 4; ++j) { const f32x4 cre_ = K.ar[j] * hre[j] - K.ai[j] * him[j], cim_ = K.ar[j] * him[j] + K.ai[j] * hre[j]; \
;         hre[j] = MFMA16K16(K.Bf[2 * j], xb_, cre_); him[j] = MFMA16K16(K.Bf[2 * j + 1], xb_, cim_); } } while (0)
; __device__ __forceinline__ unsigned s5_output(const S5C& K, const f32x4 (&hre)[4], const f32x4 (&him)[4], v2u xq, v2u zq) {
;     f32x4 y = (f32x4){0.f, 0.f, 0.f, 0.f};
; #pragma unroll
;     for (int j = 0; j < 4; ++j) y = MFMA16(K.Cf[j], pack8(hre[j], him[j]), y);
;     const f32x4 xf = (f32x4){bf_lo(xq.x), bf_hi(xq.x), bf_lo(xq.y), bf_hi(xq.y)};
;     y = y + K.dsk * xf;
;     const v2u yb = (v2u){pk2(y[0], y[1]), pk2(y[2], y[3])};
;     const f32x4 gv = MFMA16K16(K.Wv, yb, K.bv), gg = MFMA16K16(K.Wg, yb, K.bg);
; __device__ __forceinline__ void s5_prompt_task(const Args& a, const Ctx& C, int b, int g, v4u (&xv)[8]) {
;     ...
; #pragma unroll 1
;     for (int t0 = 0; t0 < 16; t0 += 4) {
; #pragma unroll
;         for (int u = 0; u < 4; ++u) { const int t = t0 + u, tok = 16 * chunk + t;
;             const v2u xq = *(const LAS v2u*)(xsl + t * 32);
;             S5_UPDATE(K, hre, him, xq);
;             *(unsigned*)((unsigned char*)Y + (row0 + tok) * DM + DA + g * 16 + 4 * q) = s5_output(K, hre, him, xq, zq[u]);
;             const size_t tn = row0 + ((t + 4 < 16) ? tok + 4 : tok);
;             zq[u] = __builtin_nontemporal_load((const v2u*)(ZBg + (size_t)(tn - row0) * 16 + 4 * q)); } }
.LBB0_988:
	ds_read2_b64 v[78:81], v163 offset1:4
	v_mov_b32_e32 v119, v5
	v_mov_b32_e32 v3, v4
	v_mul_f32_e32 v150, v88, v46
	v_mul_f32_e32 v151, v89, v47
	v_mov_b32_e32 v121, v9
	v_mov_b32_e32 v123, v13
	v_mul_f32_e32 v142, v118, v48
	v_mul_f32_e32 v143, v119, v49
	v_mul_f32_e32 v148, v88, v62
	v_mul_f32_e32 v149, v89, v63
	v_mov_b32_e32 v7, v8
	v_mul_f32_e32 v154, v92, v54
	v_mul_f32_e32 v155, v93, v55
	v_mov_b32_e32 v11, v12
	v_mul_f32_e32 v158, v96, v38
	v_mul_f32_e32 v159, v97, v39
	v_mov_b32_e32 v125, v17
	v_add_co_u32_e32 v112, vcc, s2, v106
	v_mul_f32_e32 v140, v118, v64
	v_mul_f32_e32 v141, v119, v65
	v_fma_f32 v62, v86, v62, v150
	v_fma_f32 v63, v87, v63, v151
	v_mul_f32_e32 v146, v120, v56
	v_mul_f32_e32 v147, v121, v57
	v_mul_f32_e32 v150, v122, v40
	v_mul_f32_e32 v151, v123, v41
	v_fma_f32 v64, v2, v64, v142
	v_fma_f32 v65, v3, v65, v143
	v_mul_f32_e32 v152, v92, v66
	v_mul_f32_e32 v153, v93, v67
	v_mul_f32_e32 v156, v96, v70
	v_mul_f32_e32 v157, v97, v71
	v_mov_b32_e32 v15, v16
	v_mul_f32_e32 v164, v100, v58
	v_mul_f32_e32 v165, v101, v59
	v_add_u32_e32 v108, s0, v110
	v_addc_co_u32_e32 v113, vcc, -1, v107, vcc
	s_cmp_lt_u32 s0, 12
	v_fma_f32 v46, v86, v46, -v148
	v_fma_f32 v47, v87, v47, -v149
	v_mul_f32_e32 v144, v120, v68
	v_mul_f32_e32 v145, v121, v69
	v_fma_f32 v66, v90, v66, v154
	v_fma_f32 v67, v91, v67, v155
	v_mul_f32_e32 v148, v122, v72
	v_mul_f32_e32 v149, v123, v73
	v_fma_f32 v70, v94, v70, v158
	v_fma_f32 v71, v95, v71, v159
	v_mul_f32_e32 v154, v124, v60
	v_mul_f32_e32 v155, v125, v61
	v_fma_f32 v48, v2, v48, -v140
	v_fma_f32 v49, v3, v49, -v141
	s_waitcnt lgkmcnt(0)
	v_mfma_f32_16x16x16_bf16 v[62:65], v[116:117], v[78:79], v[62:65]
	v_fma_f32 v68, v6, v68, v146
	v_fma_f32 v69, v7, v69, v147
	v_fma_f32 v72, v10, v72, v150
	v_fma_f32 v73, v11, v73, v151
	v_mul_f32_e32 v160, v100, v74
	v_mul_f32_e32 v161, v101, v75
	v_fma_f32 v54, v90, v54, -v152
	v_fma_f32 v55, v91, v55, -v153
	v_fma_f32 v38, v94, v38, -v156
	v_fma_f32 v39, v95, v39, -v157
	v_mul_f32_e32 v152, v124, v76
	v_mul_f32_e32 v153, v125, v77
	v_fma_f32 v74, v98, v74, v164
	v_fma_f32 v75, v99, v75, v165
	v_mfma_f32_16x16x16_bf16 v[46:49], v[114:115], v[78:79], v[46:49]
	v_add_u32_e32 v140, 4, v108
	s_cselect_b64 vcc, -1, 0
	v_fma_f32 v40, v10, v40, -v148
	v_fma_f32 v41, v11, v41, -v149
	v_mfma_f32_16x16x16_bf16 v[66:69], v[128:129], v[78:79], v[66:69]
	v_fma_f32 v76, v14, v76, v154
	v_fma_f32 v77, v15, v77, v155
	v_fma_f32 v58, v98, v58, -v160
	v_fma_f32 v59, v99, v59, -v161
	v_add_u32_e32 v142, 1, v108
	v_mfma_f32_16x16x16_bf16 v[70:73], v[132:133], v[78:79], v[70:73]
	v_add_u32_e32 v143, 5, v108
	v_fma_f32 v56, v6, v56, -v144
	v_fma_f32 v57, v7, v57, -v145
	v_add_u32_e32 v144, 2, v108
	v_add_u32_e32 v145, 6, v108
	v_add_u32_e32 v156, 3, v108
	v_add_u32_e32 v157, 7, v108
	v_mfma_f32_16x16x16_bf16 v[38:41], v[130:131], v[78:79], v[38:41]
	v_fma_f32 v60, v14, v60, -v152
	v_fma_f32 v61, v15, v61, -v153
	v_cndmask_b32_e32 v108, v108, v140, vcc
	v_lshlrev_b64 v[140:141], 5, v[108:109]
	v_mfma_f32_16x16x16_bf16 v[74:77], v[136:137], v[78:79], v[74:77]
	v_cndmask_b32_e32 v108, v142, v143, vcc
	v_lshl_add_u64 v[142:143], v[138:139], 0, v[140:141]
	v_lshlrev_b64 v[140:141], 5, v[108:109]
	v_mfma_f32_16x16x16_bf16 v[58:61], v[134:135], v[78:79], v[58:61]
	v_cndmask_b32_e32 v108, v144, v145, vcc
	v_mul_f32_e32 v184, v118, v64
	v_mul_f32_e32 v185, v119, v65
	v_lshlrev_b32_e32 v164, 16, v78
	v_mfma_f32_16x16x16_bf16 v[54:57], v[126:127], v[78:79], v[54:57]
	v_and_b32_e32 v165, 0xffff0000, v78
	v_lshlrev_b32_e32 v206, 16, v79
	v_and_b32_e32 v207, 0xffff0000, v79
	v_lshl_add_u64 v[78:79], v[138:139], 0, v[140:141]
	v_lshlrev_b64 v[140:141], 5, v[108:109]
	v_cndmask_b32_e32 v108, v156, v157, vcc
	v_cvt_pk_bf16_f32 v157, v68, v69
	v_mul_f32_e32 v186, v88, v62
	v_mul_f32_e32 v187, v89, v63
	v_mul_f32_e32 v188, v2, v64
	v_mul_f32_e32 v189, v3, v65
	v_mul_f32_e32 v190, v86, v62
	v_mul_f32_e32 v191, v87, v63
	v_mul_f32_e32 v192, v120, v68
	v_mul_f32_e32 v193, v121, v69
	v_mul_f32_e32 v196, v6, v68
	v_mul_f32_e32 v197, v7, v69
	v_fma_f32 v68, v2, v48, -v184
	v_fma_f32 v69, v3, v49, -v185
	v_mul_f32_e32 v184, v96, v70
	v_mul_f32_e32 v185, v97, v71
	v_cvt_pk_bf16_f32 v150, v46, v47
	v_cvt_pk_bf16_f32 v151, v48, v49
	v_cvt_pk_bf16_f32 v156, v66, v67
	v_cvt_pk_bf16_f32 v160, v70, v71
	v_mul_f32_e32 v194, v92, v66
	v_mul_f32_e32 v195, v93, v67
	v_mul_f32_e32 v198, v90, v66
	v_mul_f32_e32 v199, v91, v67
	v_mul_f32_e32 v200, v122, v72
	v_mul_f32_e32 v201, v123, v73
	v_fma_f32 v66, v86, v46, -v186
	v_fma_f32 v67, v87, v47, -v187
	v_fma_f32 v48, v118, v48, v188
	v_fma_f32 v49, v119, v49, v189
	v_fma_f32 v46, v88, v46, v190
	v_fma_f32 v47, v89, v47, v191
	v_mul_f32_e32 v186, v10, v72
	v_mul_f32_e32 v187, v11, v73
	v_mul_f32_e32 v188, v94, v70
	v_mul_f32_e32 v189, v95, v71
	v_mul_f32_e32 v190, v124, v76
	v_mul_f32_e32 v191, v125, v77
	v_fma_f32 v70, v94, v38, -v184
	v_fma_f32 v71, v95, v39, -v185
	v_mul_f32_e32 v184, v100, v74
	v_mul_f32_e32 v185, v101, v75
	v_cvt_pk_bf16_f32 v152, v62, v63
	v_cvt_pk_bf16_f32 v153, v64, v65
	v_cvt_pk_bf16_f32 v159, v40, v41
	v_cvt_pk_bf16_f32 v161, v72, v73
	v_fma_f32 v72, v10, v40, -v200
	v_fma_f32 v73, v11, v41, -v201
	v_fma_f32 v40, v122, v40, v186
	v_fma_f32 v41, v123, v41, v187
	v_fma_f32 v186, v14, v60, -v190
	v_fma_f32 v187, v15, v61, -v191
	v_fma_f32 v184, v98, v58, -v184
	v_fma_f32 v185, v99, v59, -v185
	v_cvt_pk_bf16_f32 v154, v54, v55
	v_cvt_pk_bf16_f32 v155, v56, v57
	v_cvt_pk_bf16_f32 v158, v38, v39
	v_mfma_f32_16x16x32_bf16 v[62:65], v[30:33], v[150:153], 0
	v_fma_f32 v152, v6, v56, -v192
	v_fma_f32 v153, v7, v57, -v193
; #define LAS __attribute__((address_space(3)))
; #define MFMA16(A, B, Cc) __builtin_amdgcn_mfma_f32_16x16x32_bf16((A), (B), (Cc), 0, 0, 0)
; #define MFMA16K16(A, B, Cc) __builtin_amdgcn_mfma_f32_16x16x16bf16_1k(__builtin_bit_cast(bf16x4, (A)), __builtin_bit_cast(bf16x4, (B)), (Cc), 0, 0, 0)
; __device__ __forceinline__ unsigned pk2(float lo, float hi) { return pg8::cvt_pk_bf16(lo, hi); }
; __device__ __forceinline__ float bf_lo(unsigned w) { return __uint_as_float(w << 16); }
; __device__ __forceinline__ float bf_hi(unsigned w) { return __uint_as_float(w & 0xffff0000u); }
; __device__ __forceinline__ bf16x8 pack8(f32x4 lo, f32x4 hi) { v4u w; w.x = pk2(lo[0], lo[1]); w.y = pk2(lo[2], lo[3]); w.z = pk2(hi[0], hi[1]); w.w = pk2(hi[2], hi[3]); return __builtin_bit_cast(bf16x8, w); }
; #define S5_UPDATE(K, hre, him, xq) do { const v2u xb_ = (xq); \
;     _Pragma("unroll") for (int j = 0; j < 4; ++j) { const f32x4 cre_ = K.ar[j] * hre[j] - K.ai[j] * him[j], cim_ = K.ar[j] * him[j] + K.ai[j] * hre[j]; \
;         hre[j] = MFMA16K16(K.Bf[2 * j], xb_, cre_); him[j] = MFMA16K16(K.Bf[2 * j + 1], xb_, cim_); } } while (0)
; __device__ __forceinline__ unsigned s5_output(const S5C& K, const f32x4 (&hre)[4], const f32x4 (&him)[4], v2u xq, v2u zq) {
;     f32x4 y = (f32x4){0.f, 0.f, 0.f, 0.f};
; #pragma unroll
;     for (int j = 0; j < 4; ++j) y = MFMA16(K.Cf[j], pack8(hre[j], him[j]), y);
;     const f32x4 xf = (f32x4){bf_lo(xq.x), bf_hi(xq.x), bf_lo(xq.y), bf_hi(xq.y)};
;     y = y + K.dsk * xf;
;     const v2u yb = (v2u){pk2(y[0], y[1]), pk2(y[2], y[3])};
;     const f32x4 gv = MFMA16K16(K.Wv, yb, K.bv), gg = MFMA16K16(K.Wg, yb, K.bg);
; __device__ __forceinline__ void s5_prompt_task(const Args& a, const Ctx& C, int b, int g, v4u (&xv)[8]) {
;     ...
; #pragma unroll 1
;     for (int t0 = 0; t0 < 16; t0 += 4) {
; #pragma unroll
;         for (int u = 0; u < 4; ++u) { const int t = t0 + u, tok = 16 * chunk + t;
;             const v2u xq = *(const LAS v2u*)(xsl + t * 32);
;             S5_UPDATE(K, hre, him, xq);
;             *(unsigned*)((unsigned char*)Y + (row0 + tok) * DM + DA + g * 16 + 4 * q) = s5_output(K, hre, him, xq, zq[u]);
;             const size_t tn = row0 + ((t + 4 < 16) ? tok + 4 : tok);
;             zq[u] = __builtin_nontemporal_load((const v2u*)(ZBg + (size_t)(tn - row0) * 16 + 4 * q)); } }
	v_fma_f32 v150, v90, v54, -v194
	v_fma_f32 v151, v91, v55, -v195
	v_fma_f32 v56, v120, v56, v196
	v_fma_f32 v57, v121, v57, v197
	v_fma_f32 v54, v92, v54, v198
	v_fma_f32 v55, v93, v55, v199
	v_fma_f32 v38, v96, v38, v188
	v_fma_f32 v39, v97, v39, v189
	v_mul_f32_e32 v192, v14, v76
	v_mul_f32_e32 v193, v15, v77
	v_mfma_f32_16x16x16_bf16 v[186:189], v[134:135], v[80:81], v[184:187]
	v_fma_f32 v192, v124, v60, v192
	v_fma_f32 v193, v125, v61, v193
	ds_read2_b64 v[82:85], v163 offset0:8 offset1:12
	v_cvt_pk_bf16_f32 v182, v58, v59
	v_mul_f32_e32 v184, v98, v74
	v_mul_f32_e32 v185, v99, v75
	v_mfma_f32_16x16x16_bf16 v[66:69], v[114:115], v[80:81], v[66:69]
	v_fma_f32 v190, v100, v58, v184
	v_fma_f32 v191, v101, v59, v185
	v_cvt_pk_bf16_f32 v183, v60, v61
	v_cvt_pk_bf16_f32 v185, v76, v77
	v_mfma_f32_16x16x16_bf16 v[46:49], v[116:117], v[80:81], v[46:49]
	v_lshlrev_b32_e32 v208, 16, v80
	v_and_b32_e32 v209, 0xffff0000, v80
	v_cvt_pk_bf16_f32 v184, v74, v75
	v_mfma_f32_16x16x16_bf16 v[54:57], v[128:129], v[80:81], v[54:57]
	v_lshlrev_b32_e32 v210, 16, v81
	s_nop 2
	v_mul_f32_e32 v194, v2, v48
	v_mul_f32_e32 v195, v3, v49
	v_mul_f32_e32 v196, v86, v46
	v_mul_f32_e32 v197, v87, v47
	v_mfma_f32_16x16x16_bf16 v[150:153], v[126:127], v[80:81], v[150:153]
	v_and_b32_e32 v211, 0xffff0000, v81
	v_mul_f32_e32 v198, v120, v56
	v_mul_f32_e32 v199, v121, v57
	v_cvt_pk_bf16_f32 v77, v56, v57
	v_mfma_f32_16x16x16_bf16 v[38:41], v[132:133], v[80:81], v[38:41]
	v_mul_f32_e64 v200, v92, v54
	v_mul_f32_e64 v201, v93, v55
	v_mul_f32_e32 v202, v6, v56
	v_mul_f32_e32 v203, v7, v57
	s_nop 0
	v_cvt_pk_bf16_f32 v75, v152, v153
	v_mfma_f32_16x16x16_bf16 v[190:193], v[136:137], v[80:81], v[190:193]
	v_cvt_pk_bf16_f32 v76, v54, v55
	v_mul_f32_e32 v204, v90, v54
	v_mul_f32_e32 v205, v91, v55
	v_mul_f32_e32 v216, v122, v40
	v_mul_f32_e32 v217, v123, v41
	v_mfma_f32_16x16x16_bf16 v[70:73], v[130:131], v[80:81], v[70:73]
	v_cvt_pk_bf16_f32 v74, v150, v151
	s_waitcnt lgkmcnt(0)
	v_lshlrev_b32_e32 v212, 16, v82
	v_and_b32_e32 v213, 0xffff0000, v82
	v_mfma_f32_16x16x32_bf16 v[58:61], v[50:53], v[154:157], v[62:65]
	v_mul_f32_e64 v154, v118, v48
	v_mul_f32_e64 v155, v119, v49
	v_mul_f32_e32 v156, v88, v46
	v_mul_f32_e32 v157, v89, v47
	v_fma_f32 v56, v2, v68, -v154
	v_fma_f32 v57, v3, v69, -v155
	v_cvt_pk_bf16_f32 v62, v66, v67
	v_cvt_pk_bf16_f32 v63, v68, v69
	v_cvt_pk_bf16_f32 v64, v46, v47
	v_cvt_pk_bf16_f32 v65, v48, v49
	v_mul_f32_e32 v154, v96, v38
	v_mul_f32_e32 v155, v97, v39
	v_cvt_pk_bf16_f32 v80, v70, v71
	v_mfma_f32_16x16x32_bf16 v[46:49], v[30:33], v[62:65], 0
	v_fma_f32 v64, v118, v68, v194
	v_fma_f32 v65, v119, v69, v195
	v_fma_f32 v62, v88, v66, v196
	v_fma_f32 v63, v89, v67, v197
	v_fma_f32 v68, v6, v152, -v198
	v_fma_f32 v69, v7, v153, -v199
	v_mul_f32_e32 v196, v94, v38
	v_mul_f32_e32 v197, v95, v39
	v_mul_f32_e32 v198, v124, v192
	v_mul_f32_e32 v199, v125, v193
	v_fma_f32 v54, v86, v66, -v156
	v_fma_f32 v55, v87, v67, -v157
	v_mul_f32_e32 v194, v10, v40
	v_mul_f32_e32 v195, v11, v41
	v_fma_f32 v66, v90, v150, -v200
	v_fma_f32 v67, v91, v151, -v201
	v_fma_f32 v152, v120, v152, v202
	v_fma_f32 v153, v121, v153, v203
	v_fma_f32 v154, v94, v70, -v154
	v_fma_f32 v155, v95, v71, -v155
	v_mul_f32_e32 v200, v100, v190
	v_mul_f32_e32 v201, v101, v191
	v_fma_f32 v70, v96, v70, v196
	v_fma_f32 v71, v97, v71, v197
	v_mul_f32_e32 v202, v14, v192
	v_mul_f32_e32 v203, v15, v193
	v_fma_f32 v196, v14, v188, -v198
	v_fma_f32 v197, v15, v189, -v199
	v_mul_f32_e32 v198, v98, v190
	v_mul_f32_e32 v199, v99, v191
	v_cvt_pk_bf16_f32 v81, v72, v73
	v_mfma_f32_16x16x16_bf16 v[62:65], v[116:117], v[82:83], v[62:65]
	v_fma_f32 v150, v92, v150, v204
	v_fma_f32 v151, v93, v151, v205
	v_fma_f32 v156, v10, v72, -v216
	v_fma_f32 v157, v11, v73, -v217
	v_fma_f32 v72, v122, v72, v194
	v_fma_f32 v73, v123, v73, v195
	v_fma_f32 v194, v98, v186, -v200
	v_fma_f32 v195, v99, v187, -v201
	v_fma_f32 v200, v124, v188, v202
	v_fma_f32 v201, v125, v189, v203
	v_fma_f32 v198, v100, v186, v198
	v_fma_f32 v199, v101, v187, v199
	v_lshlrev_b32_e32 v214, 16, v83
	v_and_b32_e32 v215, 0xffff0000, v83
	v_mfma_f32_16x16x16_bf16 v[54:57], v[114:115], v[82:83], v[54:57]
	v_cvt_pk_bf16_f32 v186, v186, v187
	v_cvt_pk_bf16_f32 v187, v188, v189
	v_cvt_pk_bf16_f32 v189, v192, v193
	v_mfma_f32_16x16x16_bf16 v[66:69], v[126:127], v[82:83], v[66:69]
	v_cvt_pk_bf16_f32 v188, v190, v191
	v_lshlrev_b32_e32 v144, 16, v84
	v_and_b32_e32 v145, 0xffff0000, v84
	v_mfma_f32_16x16x16_bf16 v[150:153], v[128:129], v[82:83], v[150:153]
	v_lshlrev_b32_e32 v146, 16, v85
	s_nop 2
	v_cvt_pk_bf16_f32 v190, v66, v67
	v_cvt_pk_bf16_f32 v191, v68, v69
	v_mfma_f32_16x16x16_bf16 v[154:157], v[130:131], v[82:83], v[154:157]
	v_and_b32_e32 v147, 0xffff0000, v85
	v_cvt_pk_bf16_f32 v192, v150, v151
	v_cvt_pk_bf16_f32 v193, v152, v153
	v_mfma_f32_16x16x16_bf16 v[70:73], v[132:133], v[82:83], v[70:73]
	v_mul_f32_e64 v216, v6, v152
	v_mul_f32_e64 v217, v7, v153
	v_mul_f32_e32 v218, v90, v150
	v_mul_f32_e32 v219, v91, v151
	s_nop 0
	v_cvt_pk_bf16_f32 v202, v154, v155
	v_mfma_f32_16x16x16_bf16 v[194:197], v[134:135], v[82:83], v[194:197]
	v_cvt_pk_bf16_f32 v203, v156, v157
	s_nop 0
	v_cvt_pk_bf16_f32 v204, v70, v71
	v_cvt_pk_bf16_f32 v205, v72, v73
	v_mfma_f32_16x16x16_bf16 v[198:201], v[136:137], v[82:83], v[198:201]
	v_cvt_pk_bf16_f32 v82, v38, v39
	v_cvt_pk_bf16_f32 v83, v40, v41
	v_mul_f32_e32 v220, v122, v72
	v_mul_f32_e32 v221, v123, v73
	v_mfma_f32_16x16x32_bf16 v[38:41], v[42:45], v[158:161], v[58:61]
	v_lshlrev_b64 v[148:149], 5, v[108:109]
	v_mov_b32_e32 v166, 0
	v_mov_b32_e32 v171, v109
	v_mul_f32_e32 v58, v118, v64
	v_mul_f32_e32 v59, v119, v65
; #define MFMA16(A, B, Cc) __builtin_amdgcn_mfma_f32_16x16x32_bf16((A), (B), (Cc), 0, 0, 0)
; #define MFMA16K16(A, B, Cc) __builtin_amdgcn_mfma_f32_16x16x16bf16_1k(__builtin_bit_cast(bf16x4, (A)), __builtin_bit_cast(bf16x4, (B)), (Cc), 0, 0, 0)
; __device__ __forceinline__ unsigned pk2(float lo, float hi) { return pg8::cvt_pk_bf16(lo, hi); }
; __device__ __forceinline__ float bf_lo(unsigned w) { return __uint_as_float(w << 16); }
; __device__ __forceinline__ unsigned pk4f8(float a, float b, float c, float d) { int p = __builtin_amdgcn_cvt_pk_fp8_f32(sat8(a), sat8(b), 0, false); p = __builtin_amdgcn_cvt_pk_fp8_f32(sat8(c), sat8(d), p, true); return (unsigned)p; }
; __device__ __forceinline__ float bf_hi(unsigned w) { return __uint_as_float(w & 0xffff0000u); }
; __device__ __forceinline__ bf16x8 pack8(f32x4 lo, f32x4 hi) { v4u w; w.x = pk2(lo[0], lo[1]); w.y = pk2(lo[2], lo[3]); w.z = pk2(hi[0], hi[1]); w.w = pk2(hi[2], hi[3]); return __builtin_bit_cast(bf16x8, w); }
; __device__ __forceinline__ unsigned s5_output(const S5C& K, const f32x4 (&hre)[4], const f32x4 (&him)[4], v2u xq, v2u zq) {
;     f32x4 y = (f32x4){0.f, 0.f, 0.f, 0.f};
; #pragma unroll
;     for (int j = 0; j < 4; ++j) y = MFMA16(K.Cf[j], pack8(hre[j], him[j]), y);
;     const f32x4 xf = (f32x4){bf_lo(xq.x), bf_hi(xq.x), bf_lo(xq.y), bf_hi(xq.y)};
;     y = y + K.dsk * xf;
;     const v2u yb = (v2u){pk2(y[0], y[1]), pk2(y[2], y[3])};
;     const f32x4 gv = MFMA16K16(K.Wv, yb, K.bv), gg = MFMA16K16(K.Wg, yb, K.bg);
;     const f32x4 zf = (f32x4){bf_lo(zq.x), bf_hi(zq.x), bf_lo(zq.y), bf_hi(zq.y)};
;     f32x4 o;
; #pragma unroll
;     for (int r = 0; r < 4; ++r) o[r] = gv[r] * __builtin_amdgcn_rcpf(1.0f + __expf(-gg[r])) * zf[r];
;     return pk4f8(o[0], o[1], o[2], o[3]);
	v_mul_f32_e32 v60, v88, v62
	v_mul_f32_e32 v61, v89, v63
	v_mfma_f32_16x16x32_bf16 v[158:161], v[50:53], v[74:77], v[46:49]
	v_mul_f32_e64 v74, v120, v152
	v_mul_f32_e64 v75, v121, v153
	v_mul_f32_e32 v76, v92, v150
	v_mul_f32_e32 v77, v93, v151
	v_mov_b32_e32 v176, v109
	v_cvt_pk_bf16_f32 v46, v54, v55
	v_cvt_pk_bf16_f32 v47, v56, v57
	v_cvt_pk_bf16_f32 v48, v62, v63
	v_cvt_pk_bf16_f32 v49, v64, v65
	v_mul_f32_e32 v64, v2, v64
	v_mul_f32_e32 v65, v3, v65
	v_mul_f32_e32 v62, v86, v62
	v_mul_f32_e32 v63, v87, v63
	v_mfma_f32_16x16x32_bf16 v[182:185], v[34:37], v[182:185], v[38:41]
	v_mov_b32_e32 v225, v109
	v_lshl_add_u64 v[140:141], v[138:139], 0, v[140:141]
	v_lshl_add_u64 v[148:149], v[138:139], 0, v[148:149]
	v_fma_f32 v40, v2, v56, -v58
	v_fma_f32 v41, v3, v57, -v59
	v_fma_f32 v38, v86, v54, -v60
	v_fma_f32 v39, v87, v55, -v61
	v_mfma_f32_16x16x32_bf16 v[150:153], v[30:33], v[46:49], 0
	v_mul_f32_e64 v58, v96, v70
	v_mul_f32_e64 v59, v97, v71
	v_mul_f32_e32 v60, v10, v72
	v_mul_f32_e32 v61, v11, v73
	v_mul_f32_e32 v70, v94, v70
	v_mul_f32_e32 v71, v95, v71
	v_mfma_f32_16x16x16_bf16 v[46:49], v[114:115], v[84:85], v[38:41]
	v_fma_f32 v60, v122, v156, v60
	v_fma_f32 v61, v123, v157, v61
	v_add_u32_e32 v163, 0x80, v163
	s_add_i32 s0, s0, 4
	v_fma_f32 v40, v118, v56, v64
	v_fma_f32 v41, v119, v57, v65
	v_fma_f32 v38, v88, v54, v62
	v_fma_f32 v39, v89, v55, v63
	v_mfma_f32_16x16x32_bf16 v[80:83], v[42:45], v[80:83], v[158:161]
	s_and_b64 vcc, exec, vcc
	v_mfma_f32_16x16x16_bf16 v[62:65], v[116:117], v[84:85], v[38:41]
	s_nop 0
	v_fma_f32 v158, v18, v164, v182
	v_fma_f32 v159, v19, v165, v183
	v_cvt_pk_bf16_f32 v164, v158, v159
	v_fma_f32 v40, v6, v68, -v74
	v_fma_f32 v41, v7, v69, -v75
	v_fma_f32 v38, v90, v66, -v76
	v_fma_f32 v39, v91, v67, -v77
	v_mul_f32_e32 v74, v124, v200
	v_mul_f32_e32 v75, v125, v201
	v_mul_f32_e32 v76, v100, v198
	v_mul_f32_e32 v77, v101, v199
	v_mfma_f32_16x16x16_bf16 v[54:57], v[126:127], v[84:85], v[38:41]
	v_cvt_pk_bf16_f32 v158, v46, v47
	v_cvt_pk_bf16_f32 v159, v48, v49
	v_cvt_pk_bf16_f32 v160, v62, v63
	v_fma_f32 v40, v120, v68, v216
	v_fma_f32 v41, v121, v69, v217
	v_fma_f32 v38, v92, v66, v218
	v_fma_f32 v39, v93, v67, v219
	v_mfma_f32_16x16x32_bf16 v[150:153], v[50:53], v[190:193], v[150:153]
	v_cvt_pk_bf16_f32 v161, v64, v65
	v_mfma_f32_16x16x16_bf16 v[66:69], v[128:129], v[84:85], v[38:41]
	s_nop 2
	v_fma_f32 v38, v94, v154, -v58
	v_fma_f32 v39, v95, v155, -v59
	v_fma_f32 v58, v96, v154, v70
	v_fma_f32 v59, v97, v155, v71
	v_mul_f32_e32 v154, v14, v200
	v_mul_f32_e32 v155, v15, v201
	v_fma_f32 v40, v10, v156, -v220
	v_fma_f32 v41, v11, v157, -v221
	v_mfma_f32_16x16x16_bf16 v[70:73], v[132:133], v[84:85], v[58:61]
	v_cvt_pk_bf16_f32 v156, v198, v199
	v_cvt_pk_bf16_f32 v157, v200, v201
	s_nop 0
	v_fma_f32 v60, v14, v196, -v74
	v_fma_f32 v61, v15, v197, -v75
	v_mul_f32_e32 v74, v98, v198
	v_mul_f32_e32 v75, v99, v199
	v_fma_f32 v58, v98, v194, -v76
	v_fma_f32 v59, v99, v195, -v77
	v_fma_f32 v76, v124, v196, v154
	v_fma_f32 v77, v125, v197, v155
	v_fma_f32 v74, v100, v194, v74
	v_fma_f32 v75, v101, v195, v75
	v_mfma_f32_16x16x16_bf16 v[38:41], v[130:131], v[84:85], v[38:41]
	v_cvt_pk_bf16_f32 v154, v194, v195
	v_cvt_pk_bf16_f32 v155, v196, v197
	v_cvt_pk_bf16_f32 v194, v54, v55
	v_mfma_f32_16x16x16_bf16 v[58:61], v[134:135], v[84:85], v[58:61]
	v_cvt_pk_bf16_f32 v195, v56, v57
	v_cvt_pk_bf16_f32 v196, v66, v67
	v_cvt_pk_bf16_f32 v197, v68, v69
	v_mfma_f32_16x16x16_bf16 v[74:77], v[136:137], v[84:85], v[74:77]
	v_fma_f32 v84, v20, v206, v184
	v_fma_f32 v85, v21, v207, v185
	s_nop 1
	v_cvt_pk_bf16_f32 v198, v58, v59
	v_cvt_pk_bf16_f32 v165, v84, v85
	v_mfma_f32_16x16x32_bf16 v[80:83], v[34:37], v[186:189], v[80:83]
	v_cvt_pk_bf16_f32 v186, v38, v39
	v_cvt_pk_bf16_f32 v187, v40, v41
	v_cvt_pk_bf16_f32 v188, v70, v71
	v_mfma_f32_16x16x16_bf16 v[190:193], v[104:105], v[164:165], v[26:29]
	v_cvt_pk_bf16_f32 v189, v72, v73
	s_nop 2
	v_fma_f32 v80, v18, v208, v80
	v_fma_f32 v81, v19, v209, v81
	v_cvt_pk_bf16_f32 v199, v60, v61
	v_mfma_f32_16x16x32_bf16 v[158:161], v[30:33], v[158:161], 0
	v_cvt_pk_bf16_f32 v80, v80, v81
	v_mul_f32_e32 v3, 0xbfb8aa3b, v190
	v_mul_f32_e32 v7, 0xbfb8aa3b, v191
	v_mfma_f32_16x16x32_bf16 v[150:153], v[42:45], v[202:205], v[150:153]
	v_exp_f32_e32 v3, v3
	v_exp_f32_e32 v7, v7
	v_mul_f32_e32 v11, 0xbfb8aa3b, v192
	v_mfma_f32_16x16x16_bf16 v[182:185], v[102:103], v[164:165], v[22:25]
	v_fma_f32 v164, v20, v210, v82
	v_fma_f32 v165, v21, v211, v83
	v_mul_f32_e32 v15, 0xbfb8aa3b, v193
	v_cvt_pk_bf16_f32 v81, v164, v165
	v_mfma_f32_16x16x32_bf16 v[82:85], v[50:53], v[194:197], v[158:161]
	v_exp_f32_e32 v11, v11
	v_exp_f32_e32 v15, v15
	v_add_f32_e32 v3, 1.0, v3
	v_mfma_f32_16x16x32_bf16 v[150:153], v[34:37], v[154:157], v[150:153]
	v_add_f32_e32 v7, 1.0, v7
	v_rcp_f32_e32 v3, v3
	v_rcp_f32_e32 v7, v7
	v_mfma_f32_16x16x16_bf16 v[194:197], v[104:105], v[80:81], v[26:29]
	v_cvt_pk_bf16_f32 v200, v74, v75
	s_nop 2
	v_fma_f32 v150, v18, v212, v150
	v_fma_f32 v151, v19, v213, v151
	v_cvt_pk_bf16_f32 v201, v76, v77
	v_mfma_f32_16x16x16_bf16 v[158:161], v[102:103], v[80:81], v[22:25]
	v_cvt_pk_bf16_f32 v154, v150, v151
	v_mul_f32_e32 v108, 0xbfb8aa3b, v194
	v_mul_f32_e32 v119, 0xbfb8aa3b, v195
	v_mfma_f32_16x16x32_bf16 v[80:83], v[42:45], v[186:189], v[82:85]
	v_exp_f32_e32 v108, v108
	v_exp_f32_e32 v119, v119
	v_add_f32_e32 v11, 1.0, v11
	v_fma_f32 v84, v20, v214, v152
	v_fma_f32 v85, v21, v215, v153
	v_mfma_f32_16x16x32_bf16 v[80:83], v[34:37], v[198:201], v[80:83]
	v_cvt_pk_bf16_f32 v155, v84, v85
	v_mul_f32_e32 v84, 0xbfb8aa3b, v196
	v_mul_f32_e32 v85, 0xbfb8aa3b, v197
	v_exp_f32_e32 v84, v84
	v_mfma_f32_16x16x16_bf16 v[150:153], v[102:103], v[154:155], v[22:25]
	v_exp_f32_e32 v85, v85
	v_add_f32_e32 v15, 1.0, v15
	v_rcp_f32_e32 v11, v11
	v_mfma_f32_16x16x16_bf16 v[154:157], v[104:105], v[154:155], v[26:29]
	v_rcp_f32_e32 v15, v15
	v_mul_f32_e32 v3, v182, v3
	v_mul_f32_e32 v7, v183, v7
	s_waitcnt vmcnt(0)
; #define LAS __attribute__((address_space(3)))
; #define MFMA16K16(A, B, Cc) __builtin_amdgcn_mfma_f32_16x16x16bf16_1k(__builtin_bit_cast(bf16x4, (A)), __builtin_bit_cast(bf16x4, (B)), (Cc), 0, 0, 0)
; __device__ __forceinline__ float bf_lo(unsigned w) { return __uint_as_float(w << 16); }
; __device__ __forceinline__ unsigned pk4f8(float a, float b, float c, float d) { int p = __builtin_amdgcn_cvt_pk_fp8_f32(sat8(a), sat8(b), 0, false); p = __builtin_amdgcn_cvt_pk_fp8_f32(sat8(c), sat8(d), p, true); return (unsigned)p; }
; __device__ __forceinline__ float bf_hi(unsigned w) { return __uint_as_float(w & 0xffff0000u); }
; #define S5_UPDATE(K, hre, him, xq) do { const v2u xb_ = (xq); \
;     _Pragma("unroll") for (int j = 0; j < 4; ++j) { const f32x4 cre_ = K.ar[j] * hre[j] - K.ai[j] * him[j], cim_ = K.ar[j] * him[j] + K.ai[j] * hre[j]; \
;         hre[j] = MFMA16K16(K.Bf[2 * j], xb_, cre_); him[j] = MFMA16K16(K.Bf[2 * j + 1], xb_, cim_); } } while (0)
; __device__ __forceinline__ unsigned s5_output(const S5C& K, const f32x4 (&hre)[4], const f32x4 (&him)[4], v2u xq, v2u zq) {
;     ...
;     const f32x4 gv = MFMA16K16(K.Wv, yb, K.bv), gg = MFMA16K16(K.Wg, yb, K.bg);
;     const f32x4 zf = (f32x4){bf_lo(zq.x), bf_hi(zq.x), bf_lo(zq.y), bf_hi(zq.y)};
;     f32x4 o;
; #pragma unroll
;     for (int r = 0; r < 4; ++r) o[r] = gv[r] * __builtin_amdgcn_rcpf(1.0f + __expf(-gg[r])) * zf[r];
;     return pk4f8(o[0], o[1], o[2], o[3]);
; __device__ __forceinline__ void s5_prompt_task(const Args& a, const Ctx& C, int b, int g, v4u (&xv)[8]) {
;     ...
;         for (int u = 0; u < 4; ++u) { const int t = t0 + u, tok = 16 * chunk + t;
;             const v2u xq = *(const LAS v2u*)(xsl + t * 32);
;             S5_UPDATE(K, hre, him, xq);
;             *(unsigned*)((unsigned char*)Y + (row0 + tok) * DM + DA + g * 16 + 4 * q) = s5_output(K, hre, him, xq, zq[u]);
;             const size_t tn = row0 + ((t + 4 < 16) ? tok + 4 : tok);
;             zq[u] = __builtin_nontemporal_load((const v2u*)(ZBg + (size_t)(tn - row0) * 16 + 4 * q)); } }
	v_lshlrev_b32_e32 v177, 16, v230
	v_and_b32_e32 v178, 0xffff0000, v230
	v_lshlrev_b32_e32 v179, 16, v231
	v_and_b32_e32 v180, 0xffff0000, v231
	v_lshlrev_b32_e32 v167, 16, v226
	v_and_b32_e32 v168, 0xffff0000, v226
	v_lshlrev_b32_e32 v169, 16, v227
	v_and_b32_e32 v170, 0xffff0000, v227
	v_lshlrev_b32_e32 v181, 16, v232
	v_and_b32_e32 v222, 0xffff0000, v232
	v_lshlrev_b32_e32 v223, 16, v233
	v_and_b32_e32 v224, 0xffff0000, v233
	v_lshlrev_b32_e32 v172, 16, v228
	v_and_b32_e32 v173, 0xffff0000, v228
	v_lshlrev_b32_e32 v174, 16, v229
	v_and_b32_e32 v175, 0xffff0000, v229
	v_mul_f32_e32 v3, v3, v167
	v_mul_f32_e32 v7, v7, v168
	v_add_f32_e32 v108, 1.0, v108
	v_add_f32_e32 v119, 1.0, v119
	v_add_f32_e32 v84, 1.0, v84
	v_add_f32_e32 v85, 1.0, v85
	v_med3_f32 v3, v3, s1, v111
	v_med3_f32 v7, v7, s1, v111
	v_rcp_f32_e32 v108, v108
	v_rcp_f32_e32 v119, v119
	v_rcp_f32_e32 v121, v84
	v_mul_f32_e32 v84, 0xbfb8aa3b, v154
	v_fma_f32 v82, v20, v146, v82
	v_fma_f32 v83, v21, v147, v83
	v_fma_f32 v80, v18, v144, v80
	v_fma_f32 v81, v19, v145, v81
	v_rcp_f32_e32 v123, v85
	v_cvt_pk_fp8_f32 v166, v3, v7
	v_exp_f32_e32 v3, v84
	v_cvt_pk_bf16_f32 v84, v80, v81
	v_cvt_pk_bf16_f32 v85, v82, v83
	v_mul_f32_e32 v11, v184, v11
	v_mul_f32_e32 v15, v185, v15
	v_mfma_f32_16x16x16_bf16 v[144:147], v[104:105], v[84:85], v[26:29]
	v_mul_f32_e32 v11, v11, v169
	v_mul_f32_e32 v15, v15, v170
	v_mul_f32_e32 v125, 0xbfb8aa3b, v155
	v_med3_f32 v11, v11, s1, v111
	v_med3_f32 v15, v15, s1, v111
	v_mul_f32_e32 v154, 0xbfb8aa3b, v156
	v_mul_f32_e32 v155, 0xbfb8aa3b, v157
	v_mfma_f32_16x16x16_bf16 v[80:83], v[102:103], v[84:85], v[22:25]
	v_exp_f32_e32 v7, v125
	v_mul_f32_e32 v84, v158, v108
	v_mul_f32_e32 v85, v159, v119
	v_exp_f32_e32 v125, v154
	v_exp_f32_e32 v154, v155
	v_cvt_pk_fp8_f32 v166, v11, v15 op_sel:[0,0,1]
	v_mul_f32_e32 v11, v84, v172
	v_mul_f32_e32 v15, v85, v173
	v_mul_f32_e32 v108, v160, v121
	v_mul_f32_e32 v119, v161, v123
	v_med3_f32 v11, v11, s1, v111
	v_med3_f32 v15, v15, s1, v111
	v_mul_f32_e32 v121, 0xbfb8aa3b, v144
	v_mul_f32_e32 v123, 0xbfb8aa3b, v145
	v_cvt_pk_fp8_f32 v171, v11, v15
	v_exp_f32_e32 v11, v121
	v_exp_f32_e32 v15, v123
	v_add_f32_e32 v3, 1.0, v3
	v_add_f32_e32 v7, 1.0, v7
	v_mul_f32_e32 v84, v108, v174
	v_mul_f32_e32 v85, v119, v175
	v_add_f32_e32 v108, 1.0, v125
	v_add_f32_e32 v119, 1.0, v154
	v_rcp_f32_e32 v3, v3
	v_rcp_f32_e32 v7, v7
	v_rcp_f32_e32 v108, v108
	v_rcp_f32_e32 v119, v119
	v_mul_f32_e32 v125, 0xbfb8aa3b, v146
	v_mul_f32_e32 v144, 0xbfb8aa3b, v147
	v_exp_f32_e32 v121, v125
	v_exp_f32_e32 v123, v144
	v_add_f32_e32 v11, 1.0, v11
	v_add_f32_e32 v15, 1.0, v15
	v_rcp_f32_e32 v11, v11
	v_rcp_f32_e32 v15, v15
	v_mul_f32_e32 v3, v150, v3
	v_mul_f32_e32 v7, v151, v7
	v_med3_f32 v84, v84, s1, v111
	v_med3_f32 v85, v85, s1, v111
	global_store_dword v[112:113], v166, off offset:-2048
	v_mul_f32_e32 v108, v152, v108
	v_mul_f32_e32 v112, v153, v119
	v_mul_f32_e32 v3, v3, v177
	v_mul_f32_e32 v7, v7, v178
	v_cvt_pk_fp8_f32 v171, v84, v85 op_sel:[0,0,1]
	v_mul_f32_e32 v84, v108, v179
	v_mul_f32_e32 v85, v112, v180
	v_add_f32_e32 v108, 1.0, v121
	v_add_f32_e32 v112, 1.0, v123
	v_med3_f32 v3, v3, s1, v111
	v_med3_f32 v7, v7, s1, v111
	v_rcp_f32_e32 v108, v108
	v_rcp_f32_e32 v112, v112
	v_cvt_pk_fp8_f32 v176, v3, v7
	v_mul_f32_e32 v3, v80, v11
	v_mul_f32_e32 v7, v81, v15
	v_mul_f32_e32 v3, v3, v181
	v_mul_f32_e32 v7, v7, v222
	v_med3_f32 v3, v3, s1, v111
	v_med3_f32 v7, v7, s1, v111
	v_cvt_pk_fp8_f32 v225, v3, v7
	v_mul_f32_e32 v11, v82, v108
	v_mul_f32_e32 v15, v83, v112
	v_med3_f32 v84, v84, s1, v111
	v_med3_f32 v85, v85, s1, v111
	v_mul_f32_e32 v11, v11, v223
	v_mul_f32_e32 v3, v15, v224
	v_cvt_pk_fp8_f32 v176, v84, v85 op_sel:[0,0,1]
	v_med3_f32 v7, v11, s1, v111
	v_med3_f32 v3, v3, s1, v111
	v_cvt_pk_fp8_f32 v225, v7, v3 op_sel:[0,0,1]
	global_load_dwordx2 v[226:227], v[142:143], off nt
	s_nop 0
	global_store_dword v[106:107], v171, off offset:-4096
	global_load_dwordx2 v[228:229], v[78:79], off nt
	s_nop 0
	global_store_dword v[106:107], v176, off offset:-2048
	global_load_dwordx2 v[230:231], v[140:141], off nt
	s_nop 0
	global_store_dword v[106:107], v225, off
	global_load_dwordx2 v[232:233], v[148:149], off nt
	v_lshl_add_u64 v[106:107], v[106:107], 0, s[4:5]
	s_cbranch_vccnz .LBB0_988
